# all three residual-GEMM epilogues hand-written (quad-contiguous rows via ds_bpermute, loads up front / rolling, batched row-sum atomics); tile-head vmcnt(0) dropped
# speedup vs baseline: 1.0067x; 1.0067x over previous
.LBB0_163:
	s_ashr_i32 s99, s98, 31
	s_lshl_b64 s[50:51], s[98:99], 19
	s_add_u32 s84, s8, s50
	s_addc_u32 s85, s9, s51
	s_and_b64 s[50:51], s[6:7], exec
	s_cselect_b32 s29, s85, s61
	s_cselect_b32 s31, s84, s60
	s_ashr_i32 s93, s92, 31
	s_lshl_b64 s[50:51], s[92:93], 19
	s_add_u32 s50, s10, s50
	s_addc_u32 s51, s11, s51
	s_and_b64 s[54:55], s[6:7], exec
	s_cselect_b32 s34, s51, s95
	s_cselect_b32 s47, s50, s94
	s_add_u32 vcc_lo, s60, 0x40080
	s_addc_u32 vcc_hi, s61, 0
	s_add_u32 s52, s94, 0x100
	v_mov_b32_e32 v0, 0
	s_addc_u32 s54, s95, 0
	s_mov_b32 s55, -2
	v_mov_b32_e32 v1, v0
	v_mov_b32_e32 v2, v0
	v_mov_b32_e32 v3, v0
	v_mov_b32_e32 v4, v0
	v_mov_b32_e32 v5, v0
	v_mov_b32_e32 v6, v0
	v_mov_b32_e32 v7, v0
	v_mov_b32_e32 v16, v0
	v_mov_b32_e32 v17, v0
	v_mov_b32_e32 v18, v0
	v_mov_b32_e32 v19, v0
	v_mov_b32_e32 v20, v0
	v_mov_b32_e32 v21, v0
	v_mov_b32_e32 v22, v0
	v_mov_b32_e32 v23, v0
	v_mov_b32_e32 v32, v0
	v_mov_b32_e32 v33, v0
	v_mov_b32_e32 v34, v0
	v_mov_b32_e32 v35, v0
	v_mov_b32_e32 v36, v0
	v_mov_b32_e32 v37, v0
	v_mov_b32_e32 v38, v0
	v_mov_b32_e32 v39, v0
	v_mov_b32_e32 v48, v0
	v_mov_b32_e32 v49, v0
	v_mov_b32_e32 v50, v0
	v_mov_b32_e32 v51, v0
	v_mov_b32_e32 v52, v0
	v_mov_b32_e32 v53, v0
	v_mov_b32_e32 v54, v0
	v_mov_b32_e32 v55, v0
	v_mov_b32_e32 v8, v0
	v_mov_b32_e32 v9, v0
	v_mov_b32_e32 v10, v0
	v_mov_b32_e32 v11, v0
	v_mov_b32_e32 v12, v0
	v_mov_b32_e32 v13, v0
	v_mov_b32_e32 v14, v0
	v_mov_b32_e32 v15, v0
	v_mov_b32_e32 v24, v0
	v_mov_b32_e32 v25, v0
	v_mov_b32_e32 v26, v0
	v_mov_b32_e32 v27, v0
	v_mov_b32_e32 v28, v0
	v_mov_b32_e32 v29, v0
	v_mov_b32_e32 v30, v0
	v_mov_b32_e32 v31, v0
	v_mov_b32_e32 v40, v0
	v_mov_b32_e32 v41, v0
	v_mov_b32_e32 v42, v0
	v_mov_b32_e32 v43, v0
	v_mov_b32_e32 v44, v0
	v_mov_b32_e32 v45, v0
	v_mov_b32_e32 v46, v0
	v_mov_b32_e32 v47, v0
	v_mov_b32_e32 v56, v0
	v_mov_b32_e32 v57, v0
	v_mov_b32_e32 v58, v0
	v_mov_b32_e32 v59, v0
	v_mov_b32_e32 v60, v0
	v_mov_b32_e32 v61, v0
	v_mov_b32_e32 v62, v0
	v_mov_b32_e32 v63, v0
	v_mov_b32_e32 v64, v0
	v_mov_b32_e32 v65, v0
	v_mov_b32_e32 v66, v0
	v_mov_b32_e32 v67, v0
	v_mov_b32_e32 v68, v0
	v_mov_b32_e32 v69, v0
	v_mov_b32_e32 v70, v0
	v_mov_b32_e32 v71, v0
	s_nop 0
	v_mov_b32_e32 v80, v0
	v_mov_b32_e32 v81, v0
	v_mov_b32_e32 v82, v0
	v_mov_b32_e32 v83, v0
	v_mov_b32_e32 v84, v0
	v_mov_b32_e32 v85, v0
	v_mov_b32_e32 v86, v0
	v_mov_b32_e32 v87, v0
	v_mov_b32_e32 v96, v0
	v_mov_b32_e32 v97, v0
	v_mov_b32_e32 v98, v0
	v_mov_b32_e32 v99, v0
	v_mov_b32_e32 v102, v0
	v_mov_b32_e32 v103, v0
	v_mov_b32_e32 v104, v0
	v_mov_b32_e32 v105, v0
	v_mov_b32_e32 v114, v0
	v_mov_b32_e32 v115, v0
	v_mov_b32_e32 v116, v0
	v_mov_b32_e32 v117, v0
	v_mov_b32_e32 v118, v0
	v_mov_b32_e32 v119, v0
	v_mov_b32_e32 v120, v0
	v_mov_b32_e32 v121, v0
	v_mov_b32_e32 v72, v0
	v_mov_b32_e32 v73, v0
	v_mov_b32_e32 v74, v0
	v_mov_b32_e32 v75, v0
	v_mov_b32_e32 v76, v0
	v_mov_b32_e32 v77, v0
	v_mov_b32_e32 v78, v0
	v_mov_b32_e32 v79, v0
	v_mov_b32_e32 v88, v0
	v_mov_b32_e32 v89, v0
	v_mov_b32_e32 v90, v0
	v_mov_b32_e32 v91, v0
	v_mov_b32_e32 v92, v0
	v_mov_b32_e32 v93, v0
	v_mov_b32_e32 v94, v0
	v_mov_b32_e32 v95, v0
	v_mov_b32_e32 v106, v0
	v_mov_b32_e32 v107, v0
	v_mov_b32_e32 v108, v0
	v_mov_b32_e32 v109, v0
	v_mov_b32_e32 v110, v0
	v_mov_b32_e32 v111, v0
	v_mov_b32_e32 v112, v0
	v_mov_b32_e32 v113, v0
	v_mov_b32_e32 v122, v0
	v_mov_b32_e32 v123, v0
	v_mov_b32_e32 v124, v0
	v_mov_b32_e32 v125, v0
	v_mov_b32_e32 v126, v0
	v_mov_b32_e32 v127, v0
	v_mov_b32_e32 v128, v0
	v_mov_b32_e32 v129, v0

.LBB0_167:
	s_lshl_b32 s1, s28, 8
	v_or_b32_e32 v182, s1, v197
	s_lshl_b32 s34, s30, 8
	s_andn2_b64 vcc, exec, s[76:77]
	v_ashrrev_i32_e32 v183, 31, v182
	s_cbranch_vccnz .LBB0_183
	s_add_i32 s1, s34, s65
	v_readfirstlane_b32 s4, v182
	v_mbcnt_lo_u32_b32 v100, -1, 0
	v_mbcnt_hi_u32_b32 v100, -1, v100
	s_lshl_b32 s30, s1, 11
	s_lshl_b32 s31, s4, 1
	s_add_i32 s30, s30, s31
	s_add_u32 s30, s58, s30
	s_addc_u32 s31, s59, 0
	s_lshr_b32 s28, s1, 13
	s_mul_i32 s28, s28, 0x6000000
	s_and_b32 s29, s1, 0x1fff
	s_lshl_b32 s29, s29, 12
	s_add_i32 s28, s28, s29
	s_lshl_b32 s29, s4, 2
	s_add_i32 s28, s28, s29
	s_add_u32 s28, s26, s28
	s_addc_u32 s29, s27, 0
	v_lshrrev_b32_e32 v234, 2, v100
	v_and_b32_e32 v212, 3, v100
	v_lshlrev_b32_e32 v212, 4, v212
	v_lshl_or_b32 v234, v234, 11, v212
	v_lshrrev_b32_e32 v235, 2, v100
	v_and_b32_e32 v212, 3, v100
	v_lshlrev_b32_e32 v212, 5, v212
	v_lshl_or_b32 v235, v235, 12, v212
	global_load_dwordx4 v[130:133], v234, s[30:31]
	global_load_dwordx4 v[134:137], v234, s[30:31] offset:256
	s_add_u32 s30, s30, 0x8000
	s_addc_u32 s31, s31, 0
	global_load_dwordx4 v[138:141], v234, s[30:31]
	global_load_dwordx4 v[142:145], v234, s[30:31] offset:256
	s_add_u32 s30, s30, 0x8000
	s_addc_u32 s31, s31, 0
	global_load_dwordx4 v[146:149], v234, s[30:31]
	global_load_dwordx4 v[150:153], v234, s[30:31] offset:256
	s_add_u32 s30, s30, 0x8000
	s_addc_u32 s31, s31, 0
	global_load_dwordx4 v[154:157], v234, s[30:31]
	global_load_dwordx4 v[158:161], v234, s[30:31] offset:256
	s_add_u32 s30, s30, 0x28000
	s_addc_u32 s31, s31, 0
	global_load_dwordx4 v[162:165], v234, s[30:31]
	global_load_dwordx4 v[166:169], v234, s[30:31] offset:256
	s_add_u32 s30, s30, 0x8000
	s_addc_u32 s31, s31, 0
	global_load_dwordx4 v[182:185], v234, s[30:31]
	global_load_dwordx4 v[186:189], v234, s[30:31] offset:256
	s_add_u32 s30, s30, 0x8000
	s_addc_u32 s31, s31, 0
	global_load_dwordx4 v[200:203], v234, s[30:31]
	global_load_dwordx4 v[208:211], v234, s[30:31] offset:256
	s_add_u32 s30, s30, 0x8000
	s_addc_u32 s31, s31, 0
	global_load_dwordx4 v[226:229], v234, s[30:31]
	global_load_dwordx4 v[230:233], v234, s[30:31] offset:256
	v_and_b32_e32 v212, 15, v100
	v_lshrrev_b32_e32 v213, 4, v100
	v_lshlrev_b32_e32 v213, 2, v213
	v_lshl_or_b32 v212, v212, 4, v213
	v_and_b32_e32 v192, 3, v100
	v_lshlrev_b32_e32 v192, 6, v192
	v_and_or_b32 v213, v100, 60, v192
	v_lshlrev_b32_e32 v100, 2, v100
	s_waitcnt vmcnt(15)
	ds_bpermute_b32 v130, v212, v130
	ds_bpermute_b32 v131, v212, v131
	ds_bpermute_b32 v132, v212, v132
	ds_bpermute_b32 v133, v212, v133
	s_waitcnt vmcnt(14)
	ds_bpermute_b32 v134, v212, v134
	ds_bpermute_b32 v135, v212, v135
	ds_bpermute_b32 v136, v212, v136
	ds_bpermute_b32 v137, v212, v137
	s_waitcnt lgkmcnt(4)
	v_mov_b32_e32 v192, 0
	v_mov_b32_e32 v193, 0
	v_lshlrev_b32_e32 v204, 16, v130
	v_and_b32_e32 v205, 0xffff0000, v130
	v_pk_add_f32 v[126:127], v[126:127], v[204:205]
	v_pk_fma_f32 v[192:193], v[126:127], v[126:127], v[192:193]
	v_lshlrev_b32_e32 v190, 16, v131
	v_and_b32_e32 v191, 0xffff0000, v131
	v_pk_add_f32 v[128:129], v[128:129], v[190:191]
	v_pk_fma_f32 v[192:193], v[128:129], v[128:129], v[192:193]
	v_lshlrev_b32_e32 v204, 16, v132
	v_and_b32_e32 v205, 0xffff0000, v132
	v_pk_add_f32 v[122:123], v[122:123], v[204:205]
	v_pk_fma_f32 v[192:193], v[122:123], v[122:123], v[192:193]
	v_lshlrev_b32_e32 v190, 16, v133
	v_and_b32_e32 v191, 0xffff0000, v133
	v_pk_add_f32 v[124:125], v[124:125], v[190:191]
	v_pk_fma_f32 v[192:193], v[124:125], v[124:125], v[192:193]
	ds_bpermute_b32 v126, v213, v126
	ds_bpermute_b32 v127, v213, v127
	ds_bpermute_b32 v128, v213, v128
	ds_bpermute_b32 v129, v213, v129
	ds_bpermute_b32 v122, v213, v122
	ds_bpermute_b32 v123, v213, v123
	ds_bpermute_b32 v124, v213, v124
	ds_bpermute_b32 v125, v213, v125
	s_waitcnt vmcnt(13)
	s_waitcnt lgkmcnt(11)
	ds_bpermute_b32 v138, v212, v138
	ds_bpermute_b32 v139, v212, v139
	ds_bpermute_b32 v140, v212, v140
	ds_bpermute_b32 v141, v212, v141
	s_waitcnt lgkmcnt(12)
	v_lshlrev_b32_e32 v204, 16, v134
	v_and_b32_e32 v205, 0xffff0000, v134
	v_pk_add_f32 v[118:119], v[118:119], v[204:205]
	v_pk_fma_f32 v[192:193], v[118:119], v[118:119], v[192:193]
	v_lshlrev_b32_e32 v190, 16, v135
	v_and_b32_e32 v191, 0xffff0000, v135
	v_pk_add_f32 v[120:121], v[120:121], v[190:191]
	v_pk_fma_f32 v[192:193], v[120:121], v[120:121], v[192:193]
	v_lshlrev_b32_e32 v204, 16, v136
	v_and_b32_e32 v205, 0xffff0000, v136
	v_pk_add_f32 v[114:115], v[114:115], v[204:205]
	v_pk_fma_f32 v[192:193], v[114:115], v[114:115], v[192:193]
	v_lshlrev_b32_e32 v190, 16, v137
	v_and_b32_e32 v191, 0xffff0000, v137
	v_pk_add_f32 v[116:117], v[116:117], v[190:191]
	v_pk_fma_f32 v[192:193], v[116:117], v[116:117], v[192:193]
	s_waitcnt lgkmcnt(7)
	ds_bpermute_b32 v118, v213, v118
	ds_bpermute_b32 v119, v213, v119
	ds_bpermute_b32 v120, v213, v120
	ds_bpermute_b32 v121, v213, v121
	ds_bpermute_b32 v114, v213, v114
	ds_bpermute_b32 v115, v213, v115
	ds_bpermute_b32 v116, v213, v116
	ds_bpermute_b32 v117, v213, v117
	v_add_f32_e32 v130, v192, v193
	s_waitcnt lgkmcnt(12)
	global_store_dwordx4 v235, v[126:129], s[28:29]
	global_store_dwordx4 v235, v[122:125], s[28:29] offset:16
	s_waitcnt vmcnt(14)
	s_waitcnt lgkmcnt(11)
	ds_bpermute_b32 v142, v212, v142
	ds_bpermute_b32 v143, v212, v143
	ds_bpermute_b32 v144, v212, v144
	ds_bpermute_b32 v145, v212, v145
	s_waitcnt lgkmcnt(12)
	v_mov_b32_e32 v192, 0
	v_mov_b32_e32 v193, 0
	v_lshlrev_b32_e32 v204, 16, v138
	v_and_b32_e32 v205, 0xffff0000, v138
	v_pk_add_f32 v[110:111], v[110:111], v[204:205]
	v_pk_fma_f32 v[192:193], v[110:111], v[110:111], v[192:193]
	v_lshlrev_b32_e32 v190, 16, v139
	v_and_b32_e32 v191, 0xffff0000, v139
	v_pk_add_f32 v[112:113], v[112:113], v[190:191]
	v_pk_fma_f32 v[192:193], v[112:113], v[112:113], v[192:193]
	v_lshlrev_b32_e32 v204, 16, v140
	v_and_b32_e32 v205, 0xffff0000, v140
	v_pk_add_f32 v[106:107], v[106:107], v[204:205]
	v_pk_fma_f32 v[192:193], v[106:107], v[106:107], v[192:193]
	v_lshlrev_b32_e32 v190, 16, v141
	v_and_b32_e32 v191, 0xffff0000, v141
	v_pk_add_f32 v[108:109], v[108:109], v[190:191]
	v_pk_fma_f32 v[192:193], v[108:109], v[108:109], v[192:193]
	s_waitcnt lgkmcnt(7)
	ds_bpermute_b32 v110, v213, v110
	ds_bpermute_b32 v111, v213, v111
	ds_bpermute_b32 v112, v213, v112
	ds_bpermute_b32 v113, v213, v113
	ds_bpermute_b32 v106, v213, v106
	ds_bpermute_b32 v107, v213, v107
	ds_bpermute_b32 v108, v213, v108
	ds_bpermute_b32 v109, v213, v109
	s_waitcnt lgkmcnt(12)
	global_store_dwordx4 v235, v[118:121], s[28:29] offset:512
	global_store_dwordx4 v235, v[114:117], s[28:29] offset:528
	s_add_u32 s28, s28, 0x10000
	s_addc_u32 s29, s29, 0
	s_waitcnt vmcnt(15)
	s_waitcnt lgkmcnt(11)
	ds_bpermute_b32 v146, v212, v146
	ds_bpermute_b32 v147, v212, v147
	ds_bpermute_b32 v148, v212, v148
	ds_bpermute_b32 v149, v212, v149
	s_waitcnt lgkmcnt(12)
	v_lshlrev_b32_e32 v204, 16, v142
	v_and_b32_e32 v205, 0xffff0000, v142
	v_pk_add_f32 v[102:103], v[102:103], v[204:205]
	v_pk_fma_f32 v[192:193], v[102:103], v[102:103], v[192:193]
	v_lshlrev_b32_e32 v190, 16, v143
	v_and_b32_e32 v191, 0xffff0000, v143
	v_pk_add_f32 v[104:105], v[104:105], v[190:191]
	v_pk_fma_f32 v[192:193], v[104:105], v[104:105], v[192:193]
	v_lshlrev_b32_e32 v204, 16, v144
	v_and_b32_e32 v205, 0xffff0000, v144
	v_pk_add_f32 v[96:97], v[96:97], v[204:205]
	v_pk_fma_f32 v[192:193], v[96:97], v[96:97], v[192:193]
	v_lshlrev_b32_e32 v190, 16, v145
	v_and_b32_e32 v191, 0xffff0000, v145
	v_pk_add_f32 v[98:99], v[98:99], v[190:191]
	v_pk_fma_f32 v[192:193], v[98:99], v[98:99], v[192:193]
	s_waitcnt lgkmcnt(7)
	ds_bpermute_b32 v102, v213, v102
	ds_bpermute_b32 v103, v213, v103
	ds_bpermute_b32 v104, v213, v104
	ds_bpermute_b32 v105, v213, v105
	ds_bpermute_b32 v96, v213, v96
	ds_bpermute_b32 v97, v213, v97
	ds_bpermute_b32 v98, v213, v98
	ds_bpermute_b32 v99, v213, v99
	v_add_f32_e32 v138, v192, v193
	s_waitcnt lgkmcnt(12)
	global_store_dwordx4 v235, v[110:113], s[28:29]
	global_store_dwordx4 v235, v[106:109], s[28:29] offset:16
	s_waitcnt vmcnt(16)
	s_waitcnt lgkmcnt(11)
	ds_bpermute_b32 v150, v212, v150
	ds_bpermute_b32 v151, v212, v151
	ds_bpermute_b32 v152, v212, v152
	ds_bpermute_b32 v153, v212, v153
	s_waitcnt lgkmcnt(12)
	v_mov_b32_e32 v192, 0
	v_mov_b32_e32 v193, 0
	v_lshlrev_b32_e32 v204, 16, v146
	v_and_b32_e32 v205, 0xffff0000, v146
	v_pk_add_f32 v[92:93], v[92:93], v[204:205]
	v_pk_fma_f32 v[192:193], v[92:93], v[92:93], v[192:193]
	v_lshlrev_b32_e32 v190, 16, v147
	v_and_b32_e32 v191, 0xffff0000, v147
	v_pk_add_f32 v[94:95], v[94:95], v[190:191]
	v_pk_fma_f32 v[192:193], v[94:95], v[94:95], v[192:193]
	v_lshlrev_b32_e32 v204, 16, v148
	v_and_b32_e32 v205, 0xffff0000, v148
	v_pk_add_f32 v[88:89], v[88:89], v[204:205]
	v_pk_fma_f32 v[192:193], v[88:89], v[88:89], v[192:193]
	v_lshlrev_b32_e32 v190, 16, v149
	v_and_b32_e32 v191, 0xffff0000, v149
	v_pk_add_f32 v[90:91], v[90:91], v[190:191]
	v_pk_fma_f32 v[192:193], v[90:91], v[90:91], v[192:193]
	s_waitcnt lgkmcnt(7)
	ds_bpermute_b32 v92, v213, v92
	ds_bpermute_b32 v93, v213, v93
	ds_bpermute_b32 v94, v213, v94
	ds_bpermute_b32 v95, v213, v95
	ds_bpermute_b32 v88, v213, v88
	ds_bpermute_b32 v89, v213, v89
	ds_bpermute_b32 v90, v213, v90
	ds_bpermute_b32 v91, v213, v91
	s_waitcnt lgkmcnt(12)
	global_store_dwordx4 v235, v[102:105], s[28:29] offset:512
	global_store_dwordx4 v235, v[96:99], s[28:29] offset:528
	s_add_u32 s28, s28, 0x10000
	s_addc_u32 s29, s29, 0
	s_waitcnt vmcnt(17)
	s_waitcnt lgkmcnt(11)
	ds_bpermute_b32 v154, v212, v154
	ds_bpermute_b32 v155, v212, v155
	ds_bpermute_b32 v156, v212, v156
	ds_bpermute_b32 v157, v212, v157
	s_waitcnt lgkmcnt(12)
	v_lshlrev_b32_e32 v204, 16, v150
	v_and_b32_e32 v205, 0xffff0000, v150
	v_pk_add_f32 v[84:85], v[84:85], v[204:205]
	v_pk_fma_f32 v[192:193], v[84:85], v[84:85], v[192:193]
	v_lshlrev_b32_e32 v190, 16, v151
	v_and_b32_e32 v191, 0xffff0000, v151
	v_pk_add_f32 v[86:87], v[86:87], v[190:191]
	v_pk_fma_f32 v[192:193], v[86:87], v[86:87], v[192:193]
	v_lshlrev_b32_e32 v204, 16, v152
	v_and_b32_e32 v205, 0xffff0000, v152
	v_pk_add_f32 v[80:81], v[80:81], v[204:205]
	v_pk_fma_f32 v[192:193], v[80:81], v[80:81], v[192:193]
	v_lshlrev_b32_e32 v190, 16, v153
	v_and_b32_e32 v191, 0xffff0000, v153
	v_pk_add_f32 v[82:83], v[82:83], v[190:191]
	v_pk_fma_f32 v[192:193], v[82:83], v[82:83], v[192:193]
	s_waitcnt lgkmcnt(7)
	ds_bpermute_b32 v84, v213, v84
	ds_bpermute_b32 v85, v213, v85
	ds_bpermute_b32 v86, v213, v86
	ds_bpermute_b32 v87, v213, v87
	ds_bpermute_b32 v80, v213, v80
	ds_bpermute_b32 v81, v213, v81
	ds_bpermute_b32 v82, v213, v82
	ds_bpermute_b32 v83, v213, v83
	v_add_f32_e32 v146, v192, v193
	s_waitcnt lgkmcnt(12)
	global_store_dwordx4 v235, v[92:95], s[28:29]
	global_store_dwordx4 v235, v[88:91], s[28:29] offset:16
	s_waitcnt vmcnt(18)
	s_waitcnt lgkmcnt(11)
	ds_bpermute_b32 v158, v212, v158
	ds_bpermute_b32 v159, v212, v159
	ds_bpermute_b32 v160, v212, v160
	ds_bpermute_b32 v161, v212, v161
	s_waitcnt lgkmcnt(12)
	v_mov_b32_e32 v192, 0
	v_mov_b32_e32 v193, 0
	v_lshlrev_b32_e32 v204, 16, v154
	v_and_b32_e32 v205, 0xffff0000, v154
	v_pk_add_f32 v[76:77], v[76:77], v[204:205]
	v_pk_fma_f32 v[192:193], v[76:77], v[76:77], v[192:193]
	v_lshlrev_b32_e32 v190, 16, v155
	v_and_b32_e32 v191, 0xffff0000, v155
	v_pk_add_f32 v[78:79], v[78:79], v[190:191]
	v_pk_fma_f32 v[192:193], v[78:79], v[78:79], v[192:193]
	v_lshlrev_b32_e32 v204, 16, v156
	v_and_b32_e32 v205, 0xffff0000, v156
	v_pk_add_f32 v[72:73], v[72:73], v[204:205]
	v_pk_fma_f32 v[192:193], v[72:73], v[72:73], v[192:193]
	v_lshlrev_b32_e32 v190, 16, v157
	v_and_b32_e32 v191, 0xffff0000, v157
	v_pk_add_f32 v[74:75], v[74:75], v[190:191]
	v_pk_fma_f32 v[192:193], v[74:75], v[74:75], v[192:193]
	s_waitcnt lgkmcnt(7)
	ds_bpermute_b32 v76, v213, v76
	ds_bpermute_b32 v77, v213, v77
	ds_bpermute_b32 v78, v213, v78
	ds_bpermute_b32 v79, v213, v79
	ds_bpermute_b32 v72, v213, v72
	ds_bpermute_b32 v73, v213, v73
	ds_bpermute_b32 v74, v213, v74
	ds_bpermute_b32 v75, v213, v75
	s_waitcnt lgkmcnt(12)
	global_store_dwordx4 v235, v[84:87], s[28:29] offset:512
	global_store_dwordx4 v235, v[80:83], s[28:29] offset:528
	s_add_u32 s28, s28, 0x10000
	s_addc_u32 s29, s29, 0
	s_waitcnt vmcnt(19)
	s_waitcnt lgkmcnt(11)
	ds_bpermute_b32 v162, v212, v162
	ds_bpermute_b32 v163, v212, v163
	ds_bpermute_b32 v164, v212, v164
	ds_bpermute_b32 v165, v212, v165
	s_waitcnt lgkmcnt(12)
	v_lshlrev_b32_e32 v204, 16, v158
	v_and_b32_e32 v205, 0xffff0000, v158
	v_pk_add_f32 v[68:69], v[68:69], v[204:205]
	v_pk_fma_f32 v[192:193], v[68:69], v[68:69], v[192:193]
	v_lshlrev_b32_e32 v190, 16, v159
	v_and_b32_e32 v191, 0xffff0000, v159
	v_pk_add_f32 v[70:71], v[70:71], v[190:191]
	v_pk_fma_f32 v[192:193], v[70:71], v[70:71], v[192:193]
	v_lshlrev_b32_e32 v204, 16, v160
	v_and_b32_e32 v205, 0xffff0000, v160
	v_pk_add_f32 v[64:65], v[64:65], v[204:205]
	v_pk_fma_f32 v[192:193], v[64:65], v[64:65], v[192:193]
	v_lshlrev_b32_e32 v190, 16, v161
	v_and_b32_e32 v191, 0xffff0000, v161
	v_pk_add_f32 v[66:67], v[66:67], v[190:191]
	v_pk_fma_f32 v[192:193], v[66:67], v[66:67], v[192:193]
	s_waitcnt lgkmcnt(7)
	ds_bpermute_b32 v68, v213, v68
	ds_bpermute_b32 v69, v213, v69
	ds_bpermute_b32 v70, v213, v70
	ds_bpermute_b32 v71, v213, v71
	ds_bpermute_b32 v64, v213, v64
	ds_bpermute_b32 v65, v213, v65
	ds_bpermute_b32 v66, v213, v66
	ds_bpermute_b32 v67, v213, v67
	v_add_f32_e32 v154, v192, v193
	s_waitcnt lgkmcnt(12)
	global_store_dwordx4 v235, v[76:79], s[28:29]
	global_store_dwordx4 v235, v[72:75], s[28:29] offset:16
	s_waitcnt vmcnt(20)
	s_waitcnt lgkmcnt(11)
	ds_bpermute_b32 v166, v212, v166
	ds_bpermute_b32 v167, v212, v167
	ds_bpermute_b32 v168, v212, v168
	ds_bpermute_b32 v169, v212, v169
	s_waitcnt lgkmcnt(12)
	v_mov_b32_e32 v192, 0
	v_mov_b32_e32 v193, 0
	v_lshlrev_b32_e32 v204, 16, v162
	v_and_b32_e32 v205, 0xffff0000, v162
	v_pk_add_f32 v[60:61], v[60:61], v[204:205]
	v_pk_fma_f32 v[192:193], v[60:61], v[60:61], v[192:193]
	v_lshlrev_b32_e32 v190, 16, v163
	v_and_b32_e32 v191, 0xffff0000, v163
	v_pk_add_f32 v[62:63], v[62:63], v[190:191]
	v_pk_fma_f32 v[192:193], v[62:63], v[62:63], v[192:193]
	v_lshlrev_b32_e32 v204, 16, v164
	v_and_b32_e32 v205, 0xffff0000, v164
	v_pk_add_f32 v[56:57], v[56:57], v[204:205]
	v_pk_fma_f32 v[192:193], v[56:57], v[56:57], v[192:193]
	v_lshlrev_b32_e32 v190, 16, v165
	v_and_b32_e32 v191, 0xffff0000, v165
	v_pk_add_f32 v[58:59], v[58:59], v[190:191]
	v_pk_fma_f32 v[192:193], v[58:59], v[58:59], v[192:193]
	s_waitcnt lgkmcnt(7)
	ds_bpermute_b32 v60, v213, v60
	ds_bpermute_b32 v61, v213, v61
	ds_bpermute_b32 v62, v213, v62
	ds_bpermute_b32 v63, v213, v63
	ds_bpermute_b32 v56, v213, v56
	ds_bpermute_b32 v57, v213, v57
	ds_bpermute_b32 v58, v213, v58
	ds_bpermute_b32 v59, v213, v59
	s_waitcnt lgkmcnt(12)
	global_store_dwordx4 v235, v[68:71], s[28:29] offset:512
	global_store_dwordx4 v235, v[64:67], s[28:29] offset:528
	s_add_u32 s28, s28, 0x50000
	s_addc_u32 s29, s29, 0
	s_waitcnt vmcnt(21)
	s_waitcnt lgkmcnt(11)
	ds_bpermute_b32 v182, v212, v182
	ds_bpermute_b32 v183, v212, v183
	ds_bpermute_b32 v184, v212, v184
	ds_bpermute_b32 v185, v212, v185
	s_waitcnt lgkmcnt(12)
	v_lshlrev_b32_e32 v204, 16, v166
	v_and_b32_e32 v205, 0xffff0000, v166
	v_pk_add_f32 v[52:53], v[52:53], v[204:205]
	v_pk_fma_f32 v[192:193], v[52:53], v[52:53], v[192:193]
	v_lshlrev_b32_e32 v190, 16, v167
	v_and_b32_e32 v191, 0xffff0000, v167
	v_pk_add_f32 v[54:55], v[54:55], v[190:191]
	v_pk_fma_f32 v[192:193], v[54:55], v[54:55], v[192:193]
	v_lshlrev_b32_e32 v204, 16, v168
	v_and_b32_e32 v205, 0xffff0000, v168
	v_pk_add_f32 v[48:49], v[48:49], v[204:205]
	v_pk_fma_f32 v[192:193], v[48:49], v[48:49], v[192:193]
	v_lshlrev_b32_e32 v190, 16, v169
	v_and_b32_e32 v191, 0xffff0000, v169
	v_pk_add_f32 v[50:51], v[50:51], v[190:191]
	v_pk_fma_f32 v[192:193], v[50:51], v[50:51], v[192:193]
	s_waitcnt lgkmcnt(7)
	ds_bpermute_b32 v52, v213, v52
	ds_bpermute_b32 v53, v213, v53
	ds_bpermute_b32 v54, v213, v54
	ds_bpermute_b32 v55, v213, v55
	ds_bpermute_b32 v48, v213, v48
	ds_bpermute_b32 v49, v213, v49
	ds_bpermute_b32 v50, v213, v50
	ds_bpermute_b32 v51, v213, v51
	v_add_f32_e32 v162, v192, v193
	s_waitcnt lgkmcnt(12)
	global_store_dwordx4 v235, v[60:63], s[28:29]
	global_store_dwordx4 v235, v[56:59], s[28:29] offset:16
	s_waitcnt vmcnt(22)
	s_waitcnt lgkmcnt(11)
	ds_bpermute_b32 v186, v212, v186
	ds_bpermute_b32 v187, v212, v187
	ds_bpermute_b32 v188, v212, v188
	ds_bpermute_b32 v189, v212, v189
	s_waitcnt lgkmcnt(12)
	v_mov_b32_e32 v192, 0
	v_mov_b32_e32 v193, 0
	v_lshlrev_b32_e32 v204, 16, v182
	v_and_b32_e32 v205, 0xffff0000, v182
	v_pk_add_f32 v[44:45], v[44:45], v[204:205]
	v_pk_fma_f32 v[192:193], v[44:45], v[44:45], v[192:193]
	v_lshlrev_b32_e32 v190, 16, v183
	v_and_b32_e32 v191, 0xffff0000, v183
	v_pk_add_f32 v[46:47], v[46:47], v[190:191]
	v_pk_fma_f32 v[192:193], v[46:47], v[46:47], v[192:193]
	v_lshlrev_b32_e32 v204, 16, v184
	v_and_b32_e32 v205, 0xffff0000, v184
	v_pk_add_f32 v[40:41], v[40:41], v[204:205]
	v_pk_fma_f32 v[192:193], v[40:41], v[40:41], v[192:193]
	v_lshlrev_b32_e32 v190, 16, v185
	v_and_b32_e32 v191, 0xffff0000, v185
	v_pk_add_f32 v[42:43], v[42:43], v[190:191]
	v_pk_fma_f32 v[192:193], v[42:43], v[42:43], v[192:193]
	s_waitcnt lgkmcnt(7)
	ds_bpermute_b32 v44, v213, v44
	ds_bpermute_b32 v45, v213, v45
	ds_bpermute_b32 v46, v213, v46
	ds_bpermute_b32 v47, v213, v47
	ds_bpermute_b32 v40, v213, v40
	ds_bpermute_b32 v41, v213, v41
	ds_bpermute_b32 v42, v213, v42
	ds_bpermute_b32 v43, v213, v43
	s_waitcnt lgkmcnt(12)
	global_store_dwordx4 v235, v[52:55], s[28:29] offset:512
	global_store_dwordx4 v235, v[48:51], s[28:29] offset:528
	s_add_u32 s28, s28, 0x10000
	s_addc_u32 s29, s29, 0
	s_waitcnt vmcnt(23)
	s_waitcnt lgkmcnt(11)
	ds_bpermute_b32 v200, v212, v200
	ds_bpermute_b32 v201, v212, v201
	ds_bpermute_b32 v202, v212, v202
	ds_bpermute_b32 v203, v212, v203
	s_waitcnt lgkmcnt(12)
	v_lshlrev_b32_e32 v204, 16, v186
	v_and_b32_e32 v205, 0xffff0000, v186
	v_pk_add_f32 v[36:37], v[36:37], v[204:205]
	v_pk_fma_f32 v[192:193], v[36:37], v[36:37], v[192:193]
	v_lshlrev_b32_e32 v190, 16, v187
	v_and_b32_e32 v191, 0xffff0000, v187
	v_pk_add_f32 v[38:39], v[38:39], v[190:191]
	v_pk_fma_f32 v[192:193], v[38:39], v[38:39], v[192:193]
	v_lshlrev_b32_e32 v204, 16, v188
	v_and_b32_e32 v205, 0xffff0000, v188
	v_pk_add_f32 v[32:33], v[32:33], v[204:205]
	v_pk_fma_f32 v[192:193], v[32:33], v[32:33], v[192:193]
	v_lshlrev_b32_e32 v190, 16, v189
	v_and_b32_e32 v191, 0xffff0000, v189
	v_pk_add_f32 v[34:35], v[34:35], v[190:191]
	v_pk_fma_f32 v[192:193], v[34:35], v[34:35], v[192:193]
	s_waitcnt lgkmcnt(7)
	ds_bpermute_b32 v36, v213, v36
	ds_bpermute_b32 v37, v213, v37
	ds_bpermute_b32 v38, v213, v38
	ds_bpermute_b32 v39, v213, v39
	ds_bpermute_b32 v32, v213, v32
	ds_bpermute_b32 v33, v213, v33
	ds_bpermute_b32 v34, v213, v34
	ds_bpermute_b32 v35, v213, v35
	v_add_f32_e32 v182, v192, v193
	s_waitcnt lgkmcnt(12)
	global_store_dwordx4 v235, v[44:47], s[28:29]
	global_store_dwordx4 v235, v[40:43], s[28:29] offset:16
	s_waitcnt vmcnt(24)
	s_waitcnt lgkmcnt(11)
	ds_bpermute_b32 v208, v212, v208
	ds_bpermute_b32 v209, v212, v209
	ds_bpermute_b32 v210, v212, v210
	ds_bpermute_b32 v211, v212, v211
	s_waitcnt lgkmcnt(12)
	v_mov_b32_e32 v192, 0
	v_mov_b32_e32 v193, 0
	v_lshlrev_b32_e32 v204, 16, v200
	v_and_b32_e32 v205, 0xffff0000, v200
	v_pk_add_f32 v[28:29], v[28:29], v[204:205]
	v_pk_fma_f32 v[192:193], v[28:29], v[28:29], v[192:193]
	v_lshlrev_b32_e32 v190, 16, v201
	v_and_b32_e32 v191, 0xffff0000, v201
	v_pk_add_f32 v[30:31], v[30:31], v[190:191]
	v_pk_fma_f32 v[192:193], v[30:31], v[30:31], v[192:193]
	v_lshlrev_b32_e32 v204, 16, v202
	v_and_b32_e32 v205, 0xffff0000, v202
	v_pk_add_f32 v[24:25], v[24:25], v[204:205]
	v_pk_fma_f32 v[192:193], v[24:25], v[24:25], v[192:193]
	v_lshlrev_b32_e32 v190, 16, v203
	v_and_b32_e32 v191, 0xffff0000, v203
	v_pk_add_f32 v[26:27], v[26:27], v[190:191]
	v_pk_fma_f32 v[192:193], v[26:27], v[26:27], v[192:193]
	s_waitcnt lgkmcnt(7)
	ds_bpermute_b32 v28, v213, v28
	ds_bpermute_b32 v29, v213, v29
	ds_bpermute_b32 v30, v213, v30
	ds_bpermute_b32 v31, v213, v31
	ds_bpermute_b32 v24, v213, v24
	ds_bpermute_b32 v25, v213, v25
	ds_bpermute_b32 v26, v213, v26
	ds_bpermute_b32 v27, v213, v27
	s_waitcnt lgkmcnt(12)
	global_store_dwordx4 v235, v[36:39], s[28:29] offset:512
	global_store_dwordx4 v235, v[32:35], s[28:29] offset:528
	s_add_u32 s28, s28, 0x10000
	s_addc_u32 s29, s29, 0
	s_waitcnt vmcnt(25)
	s_waitcnt lgkmcnt(11)
	ds_bpermute_b32 v226, v212, v226
	ds_bpermute_b32 v227, v212, v227
	ds_bpermute_b32 v228, v212, v228
	ds_bpermute_b32 v229, v212, v229
	s_waitcnt lgkmcnt(12)
	v_lshlrev_b32_e32 v204, 16, v208
	v_and_b32_e32 v205, 0xffff0000, v208
	v_pk_add_f32 v[20:21], v[20:21], v[204:205]
	v_pk_fma_f32 v[192:193], v[20:21], v[20:21], v[192:193]
	v_lshlrev_b32_e32 v190, 16, v209
	v_and_b32_e32 v191, 0xffff0000, v209
	v_pk_add_f32 v[22:23], v[22:23], v[190:191]
	v_pk_fma_f32 v[192:193], v[22:23], v[22:23], v[192:193]
	v_lshlrev_b32_e32 v204, 16, v210
	v_and_b32_e32 v205, 0xffff0000, v210
	v_pk_add_f32 v[16:17], v[16:17], v[204:205]
	v_pk_fma_f32 v[192:193], v[16:17], v[16:17], v[192:193]
	v_lshlrev_b32_e32 v190, 16, v211
	v_and_b32_e32 v191, 0xffff0000, v211
	v_pk_add_f32 v[18:19], v[18:19], v[190:191]
	v_pk_fma_f32 v[192:193], v[18:19], v[18:19], v[192:193]
	s_waitcnt lgkmcnt(7)
	ds_bpermute_b32 v20, v213, v20
	ds_bpermute_b32 v21, v213, v21
	ds_bpermute_b32 v22, v213, v22
	ds_bpermute_b32 v23, v213, v23
	ds_bpermute_b32 v16, v213, v16
	ds_bpermute_b32 v17, v213, v17
	ds_bpermute_b32 v18, v213, v18
	ds_bpermute_b32 v19, v213, v19
	v_add_f32_e32 v200, v192, v193
	s_waitcnt lgkmcnt(12)
	global_store_dwordx4 v235, v[28:31], s[28:29]
	global_store_dwordx4 v235, v[24:27], s[28:29] offset:16
	s_waitcnt vmcnt(26)
	s_waitcnt lgkmcnt(11)
	ds_bpermute_b32 v230, v212, v230
	ds_bpermute_b32 v231, v212, v231
	ds_bpermute_b32 v232, v212, v232
	ds_bpermute_b32 v233, v212, v233
	s_waitcnt lgkmcnt(12)
	v_mov_b32_e32 v192, 0
	v_mov_b32_e32 v193, 0
	v_lshlrev_b32_e32 v204, 16, v226
	v_and_b32_e32 v205, 0xffff0000, v226
	v_pk_add_f32 v[12:13], v[12:13], v[204:205]
	v_pk_fma_f32 v[192:193], v[12:13], v[12:13], v[192:193]
	v_lshlrev_b32_e32 v190, 16, v227
	v_and_b32_e32 v191, 0xffff0000, v227
	v_pk_add_f32 v[14:15], v[14:15], v[190:191]
	v_pk_fma_f32 v[192:193], v[14:15], v[14:15], v[192:193]
	v_lshlrev_b32_e32 v204, 16, v228
	v_and_b32_e32 v205, 0xffff0000, v228
	v_pk_add_f32 v[8:9], v[8:9], v[204:205]
	v_pk_fma_f32 v[192:193], v[8:9], v[8:9], v[192:193]
	v_lshlrev_b32_e32 v190, 16, v229
	v_and_b32_e32 v191, 0xffff0000, v229
	v_pk_add_f32 v[10:11], v[10:11], v[190:191]
	v_pk_fma_f32 v[192:193], v[10:11], v[10:11], v[192:193]
	s_waitcnt lgkmcnt(7)
	ds_bpermute_b32 v12, v213, v12
	ds_bpermute_b32 v13, v213, v13
	ds_bpermute_b32 v14, v213, v14
	ds_bpermute_b32 v15, v213, v15
	ds_bpermute_b32 v8, v213, v8
	ds_bpermute_b32 v9, v213, v9
	ds_bpermute_b32 v10, v213, v10
	ds_bpermute_b32 v11, v213, v11
	s_waitcnt lgkmcnt(12)
	global_store_dwordx4 v235, v[20:23], s[28:29] offset:512
	global_store_dwordx4 v235, v[16:19], s[28:29] offset:528
	s_add_u32 s28, s28, 0x10000
	s_addc_u32 s29, s29, 0
	s_waitcnt lgkmcnt(8)
	v_lshlrev_b32_e32 v204, 16, v230
	v_and_b32_e32 v205, 0xffff0000, v230
	v_pk_add_f32 v[4:5], v[4:5], v[204:205]
	v_pk_fma_f32 v[192:193], v[4:5], v[4:5], v[192:193]
	v_lshlrev_b32_e32 v190, 16, v231
	v_and_b32_e32 v191, 0xffff0000, v231
	v_pk_add_f32 v[6:7], v[6:7], v[190:191]
	v_pk_fma_f32 v[192:193], v[6:7], v[6:7], v[192:193]
	v_lshlrev_b32_e32 v204, 16, v232
	v_and_b32_e32 v205, 0xffff0000, v232
	v_pk_add_f32 v[0:1], v[0:1], v[204:205]
	v_pk_fma_f32 v[192:193], v[0:1], v[0:1], v[192:193]
	v_lshlrev_b32_e32 v190, 16, v233
	v_and_b32_e32 v191, 0xffff0000, v233
	v_pk_add_f32 v[2:3], v[2:3], v[190:191]
	v_pk_fma_f32 v[192:193], v[2:3], v[2:3], v[192:193]
	s_waitcnt lgkmcnt(7)
	ds_bpermute_b32 v4, v213, v4
	ds_bpermute_b32 v5, v213, v5
	ds_bpermute_b32 v6, v213, v6
	ds_bpermute_b32 v7, v213, v7
	ds_bpermute_b32 v0, v213, v0
	ds_bpermute_b32 v1, v213, v1
	ds_bpermute_b32 v2, v213, v2
	ds_bpermute_b32 v3, v213, v3
	v_add_f32_e32 v226, v192, v193
	s_waitcnt lgkmcnt(8)
	global_store_dwordx4 v235, v[12:15], s[28:29]
	global_store_dwordx4 v235, v[8:11], s[28:29] offset:16
	s_waitcnt lgkmcnt(0)
	global_store_dwordx4 v235, v[4:7], s[28:29] offset:512
	global_store_dwordx4 v235, v[0:3], s[28:29] offset:528
	ds_swizzle_b32 v131, v130 offset:swizzle(SWAP,16)
	ds_swizzle_b32 v139, v138 offset:swizzle(SWAP,16)
	ds_swizzle_b32 v147, v146 offset:swizzle(SWAP,16)
	ds_swizzle_b32 v155, v154 offset:swizzle(SWAP,16)
	ds_swizzle_b32 v163, v162 offset:swizzle(SWAP,16)
	ds_swizzle_b32 v183, v182 offset:swizzle(SWAP,16)
	ds_swizzle_b32 v201, v200 offset:swizzle(SWAP,16)
	ds_swizzle_b32 v227, v226 offset:swizzle(SWAP,16)
	s_lshl_b32 s30, s1, 2
	s_add_u32 s30, s14, s30
	s_addc_u32 s31, s15, 0
	s_waitcnt lgkmcnt(0)
	v_add_f32_e32 v130, v130, v131
	v_mov_b32_e32 v131, v130
	v_add_f32_e32 v138, v138, v139
	v_mov_b32_e32 v139, v138
	v_add_f32_e32 v146, v146, v147
	v_mov_b32_e32 v147, v146
	v_add_f32_e32 v154, v154, v155
	v_mov_b32_e32 v155, v154
	v_add_f32_e32 v162, v162, v163
	v_mov_b32_e32 v163, v162
	v_add_f32_e32 v182, v182, v183
	v_mov_b32_e32 v183, v182
	v_add_f32_e32 v200, v200, v201
	v_mov_b32_e32 v201, v200
	v_add_f32_e32 v226, v226, v227
	v_mov_b32_e32 v227, v226
	s_nop 1
	v_permlane32_swap_b32_e32 v130, v131
	v_permlane32_swap_b32_e32 v138, v139
	v_permlane32_swap_b32_e32 v146, v147
	v_permlane32_swap_b32_e32 v154, v155
	v_permlane32_swap_b32_e32 v162, v163
	v_permlane32_swap_b32_e32 v182, v183
	v_permlane32_swap_b32_e32 v200, v201
	v_permlane32_swap_b32_e32 v226, v227
	s_and_saveexec_b64 s[28:29], s[78:79]
	v_add_f32_e32 v130, v130, v131
	v_add_f32_e32 v138, v138, v139
	v_add_f32_e32 v146, v146, v147
	v_add_f32_e32 v154, v154, v155
	v_add_f32_e32 v162, v162, v163
	v_add_f32_e32 v182, v182, v183
	v_add_f32_e32 v200, v200, v201
	v_add_f32_e32 v226, v226, v227
	global_atomic_add_f32 v100, v130, s[30:31]
	global_atomic_add_f32 v100, v138, s[30:31] offset:64
	global_atomic_add_f32 v100, v146, s[30:31] offset:128
	global_atomic_add_f32 v100, v154, s[30:31] offset:192
	global_atomic_add_f32 v100, v162, s[30:31] offset:512
	global_atomic_add_f32 v100, v182, s[30:31] offset:576
	global_atomic_add_f32 v100, v200, s[30:31] offset:640
	global_atomic_add_f32 v100, v226, s[30:31] offset:704
	s_or_b64 exec, exec, s[28:29]
	s_mov_b64 s[30:31], exec
	s_branch .LBB0_218
.LBB0_183:
	s_mov_b64 s[28:29], 0
	s_cbranch_execz .LBB0_216
	v_add_u32_e32 v184, s34, v195
	v_ashrrev_i32_e32 v185, 31, v184
	v_lshlrev_b64 v[130:131], 10, v[184:185]
	s_and_b64 vcc, exec, s[80:81]
	v_or_b32_e32 v186, 16, v184
	v_lshl_add_u64 v[188:189], v[130:131], 1, s[58:59]
	s_cbranch_vccz .LBB0_215
	s_add_i32 s1, s34, s65
	v_readfirstlane_b32 s4, v182
	v_mbcnt_lo_u32_b32 v100, -1, 0
	v_mbcnt_hi_u32_b32 v100, -1, v100
	s_lshl_b32 s30, s1, 12
	s_lshl_b32 s31, s4, 2
	s_add_i32 s30, s30, s31
	s_add_u32 s30, s2, s30
	s_addc_u32 s31, s3, 0
	s_lshl_b32 s28, s1, 11
	s_lshl_b32 s29, s4, 1
	s_add_i32 s28, s28, s29
	s_add_u32 s28, s58, s28
	s_addc_u32 s29, s59, 0
	v_lshrrev_b32_e32 v234, 2, v100
	v_and_b32_e32 v212, 3, v100
	v_lshlrev_b32_e32 v212, 5, v212
	v_lshl_or_b32 v234, v234, 12, v212
	v_lshrrev_b32_e32 v235, 2, v100
	v_and_b32_e32 v212, 3, v100
	v_lshlrev_b32_e32 v212, 4, v212
	v_lshl_or_b32 v235, v235, 11, v212
	global_load_dwordx4 v[130:133], v234, s[30:31]
	global_load_dwordx4 v[134:137], v234, s[30:31] offset:16
	global_load_dwordx4 v[138:141], v234, s[30:31] offset:512
	global_load_dwordx4 v[142:145], v234, s[30:31] offset:528
	s_add_u32 s30, s30, 0x10000
	s_addc_u32 s31, s31, 0
	global_load_dwordx4 v[146:149], v234, s[30:31]
	global_load_dwordx4 v[150:153], v234, s[30:31] offset:16
	global_load_dwordx4 v[154:157], v234, s[30:31] offset:512
	global_load_dwordx4 v[158:161], v234, s[30:31] offset:528
	s_add_u32 s30, s30, 0x10000
	s_addc_u32 s31, s31, 0
	global_load_dwordx4 v[162:165], v234, s[30:31]
	global_load_dwordx4 v[166:169], v234, s[30:31] offset:16
	global_load_dwordx4 v[182:185], v234, s[30:31] offset:512
	global_load_dwordx4 v[186:189], v234, s[30:31] offset:528
	s_add_u32 s30, s30, 0x10000
	s_addc_u32 s31, s31, 0
	global_load_dwordx4 v[226:229], v234, s[30:31]
	global_load_dwordx4 v[230:233], v234, s[30:31] offset:16
	v_and_b32_e32 v212, 15, v100
	v_lshrrev_b32_e32 v213, 4, v100
	v_lshlrev_b32_e32 v213, 2, v213
	v_lshl_or_b32 v212, v212, 4, v213
	v_and_b32_e32 v192, 3, v100
	v_lshlrev_b32_e32 v192, 6, v192
	v_and_or_b32 v213, v100, 60, v192
	v_lshlrev_b32_e32 v100, 2, v100
	s_waitcnt vmcnt(12)
	ds_bpermute_b32 v130, v212, v130
	ds_bpermute_b32 v131, v212, v131
	ds_bpermute_b32 v132, v212, v132
	ds_bpermute_b32 v133, v212, v133
	ds_bpermute_b32 v134, v212, v134
	ds_bpermute_b32 v135, v212, v135
	ds_bpermute_b32 v136, v212, v136
	ds_bpermute_b32 v137, v212, v137
	s_waitcnt vmcnt(10)
	s_waitcnt lgkmcnt(7)
	ds_bpermute_b32 v138, v212, v138
	ds_bpermute_b32 v139, v212, v139
	ds_bpermute_b32 v140, v212, v140
	ds_bpermute_b32 v141, v212, v141
	ds_bpermute_b32 v142, v212, v142
	ds_bpermute_b32 v143, v212, v143
	ds_bpermute_b32 v144, v212, v144
	ds_bpermute_b32 v145, v212, v145
	s_waitcnt lgkmcnt(8)
	v_mov_b32_e32 v192, 0
	v_mov_b32_e32 v193, 0
	v_pk_add_f32 v[126:127], v[126:127], v[130:131]
	v_pk_fma_f32 v[192:193], v[126:127], v[126:127], v[192:193]
	v_pk_add_f32 v[128:129], v[128:129], v[132:133]
	v_pk_fma_f32 v[192:193], v[128:129], v[128:129], v[192:193]
	v_pk_add_f32 v[122:123], v[122:123], v[134:135]
	v_pk_fma_f32 v[192:193], v[122:123], v[122:123], v[192:193]
	v_pk_add_f32 v[124:125], v[124:125], v[136:137]
	v_pk_fma_f32 v[192:193], v[124:125], v[124:125], v[192:193]
	v_cvt_pk_bf16_f32 v126, v126, v127
	v_cvt_pk_bf16_f32 v127, v128, v129
	v_cvt_pk_bf16_f32 v128, v122, v123
	v_cvt_pk_bf16_f32 v129, v124, v125
	ds_bpermute_b32 v122, v213, v126
	ds_bpermute_b32 v123, v213, v127
	ds_bpermute_b32 v124, v213, v128
	ds_bpermute_b32 v125, v213, v129
	global_load_dwordx4 v[130:133], v234, s[30:31] offset:512
	global_load_dwordx4 v[134:137], v234, s[30:31] offset:528
	s_add_u32 s30, s30, 0x50000
	s_addc_u32 s31, s31, 0
	s_waitcnt vmcnt(10)
	s_waitcnt lgkmcnt(7)
	ds_bpermute_b32 v146, v212, v146
	ds_bpermute_b32 v147, v212, v147
	ds_bpermute_b32 v148, v212, v148
	ds_bpermute_b32 v149, v212, v149
	ds_bpermute_b32 v150, v212, v150
	ds_bpermute_b32 v151, v212, v151
	ds_bpermute_b32 v152, v212, v152
	ds_bpermute_b32 v153, v212, v153
	s_waitcnt lgkmcnt(12)
	v_pk_add_f32 v[118:119], v[118:119], v[138:139]
	v_pk_fma_f32 v[192:193], v[118:119], v[118:119], v[192:193]
	v_pk_add_f32 v[120:121], v[120:121], v[140:141]
	v_pk_fma_f32 v[192:193], v[120:121], v[120:121], v[192:193]
	v_pk_add_f32 v[114:115], v[114:115], v[142:143]
	v_pk_fma_f32 v[192:193], v[114:115], v[114:115], v[192:193]
	v_pk_add_f32 v[116:117], v[116:117], v[144:145]
	v_pk_fma_f32 v[192:193], v[116:117], v[116:117], v[192:193]
	v_cvt_pk_bf16_f32 v118, v118, v119
	v_cvt_pk_bf16_f32 v119, v120, v121
	v_cvt_pk_bf16_f32 v120, v114, v115
	v_cvt_pk_bf16_f32 v121, v116, v117
	s_waitcnt lgkmcnt(11)
	ds_bpermute_b32 v114, v213, v118
	ds_bpermute_b32 v115, v213, v119
	ds_bpermute_b32 v116, v213, v120
	ds_bpermute_b32 v117, v213, v121
	v_add_f32_e32 v190, v192, v193
	global_load_dwordx4 v[138:141], v234, s[30:31]
	global_load_dwordx4 v[142:145], v234, s[30:31] offset:16
	s_waitcnt lgkmcnt(12)
	global_store_dwordx4 v235, v[122:125], s[28:29]
	s_waitcnt vmcnt(11)
	s_waitcnt lgkmcnt(7)
	ds_bpermute_b32 v154, v212, v154
	ds_bpermute_b32 v155, v212, v155
	ds_bpermute_b32 v156, v212, v156
	ds_bpermute_b32 v157, v212, v157
	ds_bpermute_b32 v158, v212, v158
	ds_bpermute_b32 v159, v212, v159
	ds_bpermute_b32 v160, v212, v160
	ds_bpermute_b32 v161, v212, v161
	s_waitcnt lgkmcnt(12)
	v_mov_b32_e32 v192, 0
	v_mov_b32_e32 v193, 0
	v_pk_add_f32 v[110:111], v[110:111], v[146:147]
	v_pk_fma_f32 v[192:193], v[110:111], v[110:111], v[192:193]
	v_pk_add_f32 v[112:113], v[112:113], v[148:149]
	v_pk_fma_f32 v[192:193], v[112:113], v[112:113], v[192:193]
	v_pk_add_f32 v[106:107], v[106:107], v[150:151]
	v_pk_fma_f32 v[192:193], v[106:107], v[106:107], v[192:193]
	v_pk_add_f32 v[108:109], v[108:109], v[152:153]
	v_pk_fma_f32 v[192:193], v[108:109], v[108:109], v[192:193]
	v_cvt_pk_bf16_f32 v110, v110, v111
	v_cvt_pk_bf16_f32 v111, v112, v113
	v_cvt_pk_bf16_f32 v112, v106, v107
	v_cvt_pk_bf16_f32 v113, v108, v109
	s_waitcnt lgkmcnt(11)
	ds_bpermute_b32 v106, v213, v110
	ds_bpermute_b32 v107, v213, v111
	ds_bpermute_b32 v108, v213, v112
	ds_bpermute_b32 v109, v213, v113
	global_load_dwordx4 v[146:149], v234, s[30:31] offset:512
	global_load_dwordx4 v[150:153], v234, s[30:31] offset:528
	s_add_u32 s30, s30, 0x10000
	s_addc_u32 s31, s31, 0
	s_waitcnt lgkmcnt(12)
	global_store_dwordx4 v235, v[114:117], s[28:29] offset:256
	s_add_u32 s28, s28, 0x8000
	s_addc_u32 s29, s29, 0
	s_waitcnt vmcnt(12)
	s_waitcnt lgkmcnt(7)
	ds_bpermute_b32 v162, v212, v162
	ds_bpermute_b32 v163, v212, v163
	ds_bpermute_b32 v164, v212, v164
	ds_bpermute_b32 v165, v212, v165
	ds_bpermute_b32 v166, v212, v166
	ds_bpermute_b32 v167, v212, v167
	ds_bpermute_b32 v168, v212, v168
	ds_bpermute_b32 v169, v212, v169
	s_waitcnt lgkmcnt(12)
	v_pk_add_f32 v[102:103], v[102:103], v[154:155]
	v_pk_fma_f32 v[192:193], v[102:103], v[102:103], v[192:193]
	v_pk_add_f32 v[104:105], v[104:105], v[156:157]
	v_pk_fma_f32 v[192:193], v[104:105], v[104:105], v[192:193]
	v_pk_add_f32 v[96:97], v[96:97], v[158:159]
	v_pk_fma_f32 v[192:193], v[96:97], v[96:97], v[192:193]
	v_pk_add_f32 v[98:99], v[98:99], v[160:161]
	v_pk_fma_f32 v[192:193], v[98:99], v[98:99], v[192:193]
	v_cvt_pk_bf16_f32 v102, v102, v103
	v_cvt_pk_bf16_f32 v103, v104, v105
	v_cvt_pk_bf16_f32 v104, v96, v97
	v_cvt_pk_bf16_f32 v105, v98, v99
	s_waitcnt lgkmcnt(11)
	ds_bpermute_b32 v96, v213, v102
	ds_bpermute_b32 v97, v213, v103
	ds_bpermute_b32 v98, v213, v104
	ds_bpermute_b32 v99, v213, v105
	v_add_f32_e32 v191, v192, v193
	global_load_dwordx4 v[154:157], v234, s[30:31]
	global_load_dwordx4 v[158:161], v234, s[30:31] offset:16
	s_waitcnt lgkmcnt(12)
	global_store_dwordx4 v235, v[106:109], s[28:29]
	s_waitcnt vmcnt(13)
	s_waitcnt lgkmcnt(7)
	ds_bpermute_b32 v182, v212, v182
	ds_bpermute_b32 v183, v212, v183
	ds_bpermute_b32 v184, v212, v184
	ds_bpermute_b32 v185, v212, v185
	ds_bpermute_b32 v186, v212, v186
	ds_bpermute_b32 v187, v212, v187
	ds_bpermute_b32 v188, v212, v188
	ds_bpermute_b32 v189, v212, v189
	s_waitcnt lgkmcnt(12)
	v_mov_b32_e32 v192, 0
	v_mov_b32_e32 v193, 0
	v_pk_add_f32 v[92:93], v[92:93], v[162:163]
	v_pk_fma_f32 v[192:193], v[92:93], v[92:93], v[192:193]
	v_pk_add_f32 v[94:95], v[94:95], v[164:165]
	v_pk_fma_f32 v[192:193], v[94:95], v[94:95], v[192:193]
	v_pk_add_f32 v[88:89], v[88:89], v[166:167]
	v_pk_fma_f32 v[192:193], v[88:89], v[88:89], v[192:193]
	v_pk_add_f32 v[90:91], v[90:91], v[168:169]
	v_pk_fma_f32 v[192:193], v[90:91], v[90:91], v[192:193]
	v_cvt_pk_bf16_f32 v92, v92, v93
	v_cvt_pk_bf16_f32 v93, v94, v95
	v_cvt_pk_bf16_f32 v94, v88, v89
	v_cvt_pk_bf16_f32 v95, v90, v91
	s_waitcnt lgkmcnt(11)
	ds_bpermute_b32 v88, v213, v92
	ds_bpermute_b32 v89, v213, v93
	ds_bpermute_b32 v90, v213, v94
	ds_bpermute_b32 v91, v213, v95
	global_load_dwordx4 v[162:165], v234, s[30:31] offset:512
	global_load_dwordx4 v[166:169], v234, s[30:31] offset:528
	s_add_u32 s30, s30, 0x10000
	s_addc_u32 s31, s31, 0
	s_waitcnt lgkmcnt(12)
	global_store_dwordx4 v235, v[96:99], s[28:29] offset:256
	s_add_u32 s28, s28, 0x8000
	s_addc_u32 s29, s29, 0
	s_waitcnt vmcnt(14)
	s_waitcnt lgkmcnt(7)
	ds_bpermute_b32 v226, v212, v226
	ds_bpermute_b32 v227, v212, v227
	ds_bpermute_b32 v228, v212, v228
	ds_bpermute_b32 v229, v212, v229
	ds_bpermute_b32 v230, v212, v230
	ds_bpermute_b32 v231, v212, v231
	ds_bpermute_b32 v232, v212, v232
	ds_bpermute_b32 v233, v212, v233
	s_waitcnt lgkmcnt(12)
	v_pk_add_f32 v[84:85], v[84:85], v[182:183]
	v_pk_fma_f32 v[192:193], v[84:85], v[84:85], v[192:193]
	v_pk_add_f32 v[86:87], v[86:87], v[184:185]
	v_pk_fma_f32 v[192:193], v[86:87], v[86:87], v[192:193]
	v_pk_add_f32 v[80:81], v[80:81], v[186:187]
	v_pk_fma_f32 v[192:193], v[80:81], v[80:81], v[192:193]
	v_pk_add_f32 v[82:83], v[82:83], v[188:189]
	v_pk_fma_f32 v[192:193], v[82:83], v[82:83], v[192:193]
	v_cvt_pk_bf16_f32 v84, v84, v85
	v_cvt_pk_bf16_f32 v85, v86, v87
	v_cvt_pk_bf16_f32 v86, v80, v81
	v_cvt_pk_bf16_f32 v87, v82, v83
	s_waitcnt lgkmcnt(11)
	ds_bpermute_b32 v80, v213, v84
	ds_bpermute_b32 v81, v213, v85
	ds_bpermute_b32 v82, v213, v86
	ds_bpermute_b32 v83, v213, v87
	v_add_f32_e32 v204, v192, v193
	global_load_dwordx4 v[182:185], v234, s[30:31]
	global_load_dwordx4 v[186:189], v234, s[30:31] offset:16
	s_waitcnt lgkmcnt(12)
	global_store_dwordx4 v235, v[88:91], s[28:29]
	s_waitcnt vmcnt(15)
	s_waitcnt lgkmcnt(7)
	ds_bpermute_b32 v130, v212, v130
	ds_bpermute_b32 v131, v212, v131
	ds_bpermute_b32 v132, v212, v132
	ds_bpermute_b32 v133, v212, v133
	ds_bpermute_b32 v134, v212, v134
	ds_bpermute_b32 v135, v212, v135
	ds_bpermute_b32 v136, v212, v136
	ds_bpermute_b32 v137, v212, v137
	s_waitcnt lgkmcnt(12)
	v_mov_b32_e32 v192, 0
	v_mov_b32_e32 v193, 0
	v_pk_add_f32 v[76:77], v[76:77], v[226:227]
	v_pk_fma_f32 v[192:193], v[76:77], v[76:77], v[192:193]
	v_pk_add_f32 v[78:79], v[78:79], v[228:229]
	v_pk_fma_f32 v[192:193], v[78:79], v[78:79], v[192:193]
	v_pk_add_f32 v[72:73], v[72:73], v[230:231]
	v_pk_fma_f32 v[192:193], v[72:73], v[72:73], v[192:193]
	v_pk_add_f32 v[74:75], v[74:75], v[232:233]
	v_pk_fma_f32 v[192:193], v[74:75], v[74:75], v[192:193]
	v_cvt_pk_bf16_f32 v76, v76, v77
	v_cvt_pk_bf16_f32 v77, v78, v79
	v_cvt_pk_bf16_f32 v78, v72, v73
	v_cvt_pk_bf16_f32 v79, v74, v75
	s_waitcnt lgkmcnt(11)
	ds_bpermute_b32 v72, v213, v76
	ds_bpermute_b32 v73, v213, v77
	ds_bpermute_b32 v74, v213, v78
	ds_bpermute_b32 v75, v213, v79
	global_load_dwordx4 v[226:229], v234, s[30:31] offset:512
	global_load_dwordx4 v[230:233], v234, s[30:31] offset:528
	s_add_u32 s30, s30, 0x10000
	s_addc_u32 s31, s31, 0
	s_waitcnt lgkmcnt(12)
	global_store_dwordx4 v235, v[80:83], s[28:29] offset:256
	s_add_u32 s28, s28, 0x8000
	s_addc_u32 s29, s29, 0
	s_waitcnt vmcnt(16)
	s_waitcnt lgkmcnt(7)
	ds_bpermute_b32 v138, v212, v138
	ds_bpermute_b32 v139, v212, v139
	ds_bpermute_b32 v140, v212, v140
	ds_bpermute_b32 v141, v212, v141
	ds_bpermute_b32 v142, v212, v142
	ds_bpermute_b32 v143, v212, v143
	ds_bpermute_b32 v144, v212, v144
	ds_bpermute_b32 v145, v212, v145
	s_waitcnt lgkmcnt(12)
	v_pk_add_f32 v[68:69], v[68:69], v[130:131]
	v_pk_fma_f32 v[192:193], v[68:69], v[68:69], v[192:193]
	v_pk_add_f32 v[70:71], v[70:71], v[132:133]
	v_pk_fma_f32 v[192:193], v[70:71], v[70:71], v[192:193]
	v_pk_add_f32 v[64:65], v[64:65], v[134:135]
	v_pk_fma_f32 v[192:193], v[64:65], v[64:65], v[192:193]
	v_pk_add_f32 v[66:67], v[66:67], v[136:137]
	v_pk_fma_f32 v[192:193], v[66:67], v[66:67], v[192:193]
	v_cvt_pk_bf16_f32 v68, v68, v69
	v_cvt_pk_bf16_f32 v69, v70, v71
	v_cvt_pk_bf16_f32 v70, v64, v65
	v_cvt_pk_bf16_f32 v71, v66, v67
	s_waitcnt lgkmcnt(11)
	ds_bpermute_b32 v64, v213, v68
	ds_bpermute_b32 v65, v213, v69
	ds_bpermute_b32 v66, v213, v70
	ds_bpermute_b32 v67, v213, v71
	v_add_f32_e32 v205, v192, v193
	global_load_dwordx4 v[130:133], v234, s[30:31]
	global_load_dwordx4 v[134:137], v234, s[30:31] offset:16
	s_waitcnt lgkmcnt(12)
	global_store_dwordx4 v235, v[72:75], s[28:29]
	s_waitcnt vmcnt(16)
	s_waitcnt lgkmcnt(7)
	ds_bpermute_b32 v146, v212, v146
	ds_bpermute_b32 v147, v212, v147
	ds_bpermute_b32 v148, v212, v148
	ds_bpermute_b32 v149, v212, v149
	ds_bpermute_b32 v150, v212, v150
	ds_bpermute_b32 v151, v212, v151
	ds_bpermute_b32 v152, v212, v152
	ds_bpermute_b32 v153, v212, v153
	s_waitcnt lgkmcnt(12)
	v_mov_b32_e32 v192, 0
	v_mov_b32_e32 v193, 0
	v_pk_add_f32 v[60:61], v[60:61], v[138:139]
	v_pk_fma_f32 v[192:193], v[60:61], v[60:61], v[192:193]
	v_pk_add_f32 v[62:63], v[62:63], v[140:141]
	v_pk_fma_f32 v[192:193], v[62:63], v[62:63], v[192:193]
	v_pk_add_f32 v[56:57], v[56:57], v[142:143]
	v_pk_fma_f32 v[192:193], v[56:57], v[56:57], v[192:193]
	v_pk_add_f32 v[58:59], v[58:59], v[144:145]
	v_pk_fma_f32 v[192:193], v[58:59], v[58:59], v[192:193]
	v_cvt_pk_bf16_f32 v60, v60, v61
	v_cvt_pk_bf16_f32 v61, v62, v63
	v_cvt_pk_bf16_f32 v62, v56, v57
	v_cvt_pk_bf16_f32 v63, v58, v59
	s_waitcnt lgkmcnt(11)
	ds_bpermute_b32 v56, v213, v60
	ds_bpermute_b32 v57, v213, v61
	ds_bpermute_b32 v58, v213, v62
	ds_bpermute_b32 v59, v213, v63
	global_load_dwordx4 v[138:141], v234, s[30:31] offset:512
	global_load_dwordx4 v[142:145], v234, s[30:31] offset:528
	s_waitcnt lgkmcnt(12)
	global_store_dwordx4 v235, v[64:67], s[28:29] offset:256
	s_add_u32 s28, s28, 0x28000
	s_addc_u32 s29, s29, 0
	s_waitcnt vmcnt(16)
	s_waitcnt lgkmcnt(7)
	ds_bpermute_b32 v154, v212, v154
	ds_bpermute_b32 v155, v212, v155
	ds_bpermute_b32 v156, v212, v156
	ds_bpermute_b32 v157, v212, v157
	ds_bpermute_b32 v158, v212, v158
	ds_bpermute_b32 v159, v212, v159
	ds_bpermute_b32 v160, v212, v160
	ds_bpermute_b32 v161, v212, v161
	s_waitcnt lgkmcnt(12)
	v_pk_add_f32 v[52:53], v[52:53], v[146:147]
	v_pk_fma_f32 v[192:193], v[52:53], v[52:53], v[192:193]
	v_pk_add_f32 v[54:55], v[54:55], v[148:149]
	v_pk_fma_f32 v[192:193], v[54:55], v[54:55], v[192:193]
	v_pk_add_f32 v[48:49], v[48:49], v[150:151]
	v_pk_fma_f32 v[192:193], v[48:49], v[48:49], v[192:193]
	v_pk_add_f32 v[50:51], v[50:51], v[152:153]
	v_pk_fma_f32 v[192:193], v[50:51], v[50:51], v[192:193]
	v_cvt_pk_bf16_f32 v52, v52, v53
	v_cvt_pk_bf16_f32 v53, v54, v55
	v_cvt_pk_bf16_f32 v54, v48, v49
	v_cvt_pk_bf16_f32 v55, v50, v51
	s_waitcnt lgkmcnt(11)
	ds_bpermute_b32 v48, v213, v52
	ds_bpermute_b32 v49, v213, v53
	ds_bpermute_b32 v50, v213, v54
	ds_bpermute_b32 v51, v213, v55
	v_add_f32_e32 v200, v192, v193
	s_waitcnt lgkmcnt(12)
	global_store_dwordx4 v235, v[56:59], s[28:29]
	s_waitcnt vmcnt(14)
	s_waitcnt lgkmcnt(7)
	ds_bpermute_b32 v162, v212, v162
	ds_bpermute_b32 v163, v212, v163
	ds_bpermute_b32 v164, v212, v164
	ds_bpermute_b32 v165, v212, v165
	ds_bpermute_b32 v166, v212, v166
	ds_bpermute_b32 v167, v212, v167
	ds_bpermute_b32 v168, v212, v168
	ds_bpermute_b32 v169, v212, v169
	s_waitcnt lgkmcnt(12)
	v_mov_b32_e32 v192, 0
	v_mov_b32_e32 v193, 0
	v_pk_add_f32 v[44:45], v[44:45], v[154:155]
	v_pk_fma_f32 v[192:193], v[44:45], v[44:45], v[192:193]
	v_pk_add_f32 v[46:47], v[46:47], v[156:157]
	v_pk_fma_f32 v[192:193], v[46:47], v[46:47], v[192:193]
	v_pk_add_f32 v[40:41], v[40:41], v[158:159]
	v_pk_fma_f32 v[192:193], v[40:41], v[40:41], v[192:193]
	v_pk_add_f32 v[42:43], v[42:43], v[160:161]
	v_pk_fma_f32 v[192:193], v[42:43], v[42:43], v[192:193]
	v_cvt_pk_bf16_f32 v44, v44, v45
	v_cvt_pk_bf16_f32 v45, v46, v47
	v_cvt_pk_bf16_f32 v46, v40, v41
	v_cvt_pk_bf16_f32 v47, v42, v43
	s_waitcnt lgkmcnt(11)
	ds_bpermute_b32 v40, v213, v44
	ds_bpermute_b32 v41, v213, v45
	ds_bpermute_b32 v42, v213, v46
	ds_bpermute_b32 v43, v213, v47
	s_waitcnt lgkmcnt(12)
	global_store_dwordx4 v235, v[48:51], s[28:29] offset:256
	s_add_u32 s28, s28, 0x8000
	s_addc_u32 s29, s29, 0
	s_waitcnt vmcnt(12)
	s_waitcnt lgkmcnt(7)
	ds_bpermute_b32 v182, v212, v182
	ds_bpermute_b32 v183, v212, v183
	ds_bpermute_b32 v184, v212, v184
	ds_bpermute_b32 v185, v212, v185
	ds_bpermute_b32 v186, v212, v186
	ds_bpermute_b32 v187, v212, v187
	ds_bpermute_b32 v188, v212, v188
	ds_bpermute_b32 v189, v212, v189
	s_waitcnt lgkmcnt(12)
	v_pk_add_f32 v[36:37], v[36:37], v[162:163]
	v_pk_fma_f32 v[192:193], v[36:37], v[36:37], v[192:193]
	v_pk_add_f32 v[38:39], v[38:39], v[164:165]
	v_pk_fma_f32 v[192:193], v[38:39], v[38:39], v[192:193]
	v_pk_add_f32 v[32:33], v[32:33], v[166:167]
	v_pk_fma_f32 v[192:193], v[32:33], v[32:33], v[192:193]
	v_pk_add_f32 v[34:35], v[34:35], v[168:169]
	v_pk_fma_f32 v[192:193], v[34:35], v[34:35], v[192:193]
	v_cvt_pk_bf16_f32 v36, v36, v37
	v_cvt_pk_bf16_f32 v37, v38, v39
	v_cvt_pk_bf16_f32 v38, v32, v33
	v_cvt_pk_bf16_f32 v39, v34, v35
	s_waitcnt lgkmcnt(11)
	ds_bpermute_b32 v32, v213, v36
	ds_bpermute_b32 v33, v213, v37
	ds_bpermute_b32 v34, v213, v38
	ds_bpermute_b32 v35, v213, v39
	v_add_f32_e32 v201, v192, v193
	s_waitcnt lgkmcnt(12)
	global_store_dwordx4 v235, v[40:43], s[28:29]
	s_waitcnt vmcnt(10)
	s_waitcnt lgkmcnt(7)
	ds_bpermute_b32 v226, v212, v226
	ds_bpermute_b32 v227, v212, v227
	ds_bpermute_b32 v228, v212, v228
	ds_bpermute_b32 v229, v212, v229
	ds_bpermute_b32 v230, v212, v230
	ds_bpermute_b32 v231, v212, v231
	ds_bpermute_b32 v232, v212, v232
	ds_bpermute_b32 v233, v212, v233
	s_waitcnt lgkmcnt(12)
	v_mov_b32_e32 v192, 0
	v_mov_b32_e32 v193, 0
	v_pk_add_f32 v[28:29], v[28:29], v[182:183]
	v_pk_fma_f32 v[192:193], v[28:29], v[28:29], v[192:193]
	v_pk_add_f32 v[30:31], v[30:31], v[184:185]
	v_pk_fma_f32 v[192:193], v[30:31], v[30:31], v[192:193]
	v_pk_add_f32 v[24:25], v[24:25], v[186:187]
	v_pk_fma_f32 v[192:193], v[24:25], v[24:25], v[192:193]
	v_pk_add_f32 v[26:27], v[26:27], v[188:189]
	v_pk_fma_f32 v[192:193], v[26:27], v[26:27], v[192:193]
	v_cvt_pk_bf16_f32 v28, v28, v29
	v_cvt_pk_bf16_f32 v29, v30, v31
	v_cvt_pk_bf16_f32 v30, v24, v25
	v_cvt_pk_bf16_f32 v31, v26, v27
	s_waitcnt lgkmcnt(11)
	ds_bpermute_b32 v24, v213, v28
	ds_bpermute_b32 v25, v213, v29
	ds_bpermute_b32 v26, v213, v30
	ds_bpermute_b32 v27, v213, v31
	s_waitcnt lgkmcnt(12)
	global_store_dwordx4 v235, v[32:35], s[28:29] offset:256
	s_add_u32 s28, s28, 0x8000
	s_addc_u32 s29, s29, 0
	s_waitcnt vmcnt(8)
	s_waitcnt lgkmcnt(7)
	ds_bpermute_b32 v130, v212, v130
	ds_bpermute_b32 v131, v212, v131
	ds_bpermute_b32 v132, v212, v132
	ds_bpermute_b32 v133, v212, v133
	ds_bpermute_b32 v134, v212, v134
	ds_bpermute_b32 v135, v212, v135
	ds_bpermute_b32 v136, v212, v136
	ds_bpermute_b32 v137, v212, v137
	s_waitcnt lgkmcnt(12)
	v_pk_add_f32 v[20:21], v[20:21], v[226:227]
	v_pk_fma_f32 v[192:193], v[20:21], v[20:21], v[192:193]
	v_pk_add_f32 v[22:23], v[22:23], v[228:229]
	v_pk_fma_f32 v[192:193], v[22:23], v[22:23], v[192:193]
	v_pk_add_f32 v[16:17], v[16:17], v[230:231]
	v_pk_fma_f32 v[192:193], v[16:17], v[16:17], v[192:193]
	v_pk_add_f32 v[18:19], v[18:19], v[232:233]
	v_pk_fma_f32 v[192:193], v[18:19], v[18:19], v[192:193]
	v_cvt_pk_bf16_f32 v20, v20, v21
	v_cvt_pk_bf16_f32 v21, v22, v23
	v_cvt_pk_bf16_f32 v22, v16, v17
	v_cvt_pk_bf16_f32 v23, v18, v19
	s_waitcnt lgkmcnt(11)
	ds_bpermute_b32 v16, v213, v20
	ds_bpermute_b32 v17, v213, v21
	ds_bpermute_b32 v18, v213, v22
	ds_bpermute_b32 v19, v213, v23
	v_add_f32_e32 v202, v192, v193
	s_waitcnt lgkmcnt(12)
	global_store_dwordx4 v235, v[24:27], s[28:29]
	s_waitcnt vmcnt(6)
	s_waitcnt lgkmcnt(7)
	ds_bpermute_b32 v138, v212, v138
	ds_bpermute_b32 v139, v212, v139
	ds_bpermute_b32 v140, v212, v140
	ds_bpermute_b32 v141, v212, v141
	ds_bpermute_b32 v142, v212, v142
	ds_bpermute_b32 v143, v212, v143
	ds_bpermute_b32 v144, v212, v144
	ds_bpermute_b32 v145, v212, v145
	s_waitcnt lgkmcnt(12)
	v_mov_b32_e32 v192, 0
	v_mov_b32_e32 v193, 0
	v_pk_add_f32 v[12:13], v[12:13], v[130:131]
	v_pk_fma_f32 v[192:193], v[12:13], v[12:13], v[192:193]
	v_pk_add_f32 v[14:15], v[14:15], v[132:133]
	v_pk_fma_f32 v[192:193], v[14:15], v[14:15], v[192:193]
	v_pk_add_f32 v[8:9], v[8:9], v[134:135]
	v_pk_fma_f32 v[192:193], v[8:9], v[8:9], v[192:193]
	v_pk_add_f32 v[10:11], v[10:11], v[136:137]
	v_pk_fma_f32 v[192:193], v[10:11], v[10:11], v[192:193]
	v_cvt_pk_bf16_f32 v12, v12, v13
	v_cvt_pk_bf16_f32 v13, v14, v15
	v_cvt_pk_bf16_f32 v14, v8, v9
	v_cvt_pk_bf16_f32 v15, v10, v11
	s_waitcnt lgkmcnt(11)
	ds_bpermute_b32 v8, v213, v12
	ds_bpermute_b32 v9, v213, v13
	ds_bpermute_b32 v10, v213, v14
	ds_bpermute_b32 v11, v213, v15
	s_waitcnt lgkmcnt(12)
	global_store_dwordx4 v235, v[16:19], s[28:29] offset:256
	s_add_u32 s28, s28, 0x8000
	s_addc_u32 s29, s29, 0
	s_waitcnt lgkmcnt(4)
	v_pk_add_f32 v[4:5], v[4:5], v[138:139]
	v_pk_fma_f32 v[192:193], v[4:5], v[4:5], v[192:193]
	v_pk_add_f32 v[6:7], v[6:7], v[140:141]
	v_pk_fma_f32 v[192:193], v[6:7], v[6:7], v[192:193]
	v_pk_add_f32 v[0:1], v[0:1], v[142:143]
	v_pk_fma_f32 v[192:193], v[0:1], v[0:1], v[192:193]
	v_pk_add_f32 v[2:3], v[2:3], v[144:145]
	v_pk_fma_f32 v[192:193], v[2:3], v[2:3], v[192:193]
	v_cvt_pk_bf16_f32 v4, v4, v5
	v_cvt_pk_bf16_f32 v5, v6, v7
	v_cvt_pk_bf16_f32 v6, v0, v1
	v_cvt_pk_bf16_f32 v7, v2, v3
	ds_bpermute_b32 v0, v213, v4
	ds_bpermute_b32 v1, v213, v5
	ds_bpermute_b32 v2, v213, v6
	ds_bpermute_b32 v3, v213, v7
	v_add_f32_e32 v203, v192, v193
	s_waitcnt lgkmcnt(4)
	global_store_dwordx4 v235, v[8:11], s[28:29]
	s_waitcnt lgkmcnt(0)
	global_store_dwordx4 v235, v[0:3], s[28:29] offset:256
	ds_swizzle_b32 v130, v190 offset:swizzle(SWAP,16)
	ds_swizzle_b32 v131, v191 offset:swizzle(SWAP,16)
	ds_swizzle_b32 v132, v204 offset:swizzle(SWAP,16)
	ds_swizzle_b32 v133, v205 offset:swizzle(SWAP,16)
	ds_swizzle_b32 v134, v200 offset:swizzle(SWAP,16)
	ds_swizzle_b32 v135, v201 offset:swizzle(SWAP,16)
	ds_swizzle_b32 v136, v202 offset:swizzle(SWAP,16)
	ds_swizzle_b32 v137, v203 offset:swizzle(SWAP,16)
	s_lshl_b32 s30, s1, 2
	s_add_u32 s30, s14, s30
	s_addc_u32 s31, s15, 0
	s_waitcnt lgkmcnt(0)
	v_add_f32_e32 v190, v190, v130
	v_mov_b32_e32 v130, v190
	v_add_f32_e32 v191, v191, v131
	v_mov_b32_e32 v131, v191
	v_add_f32_e32 v204, v204, v132
	v_mov_b32_e32 v132, v204
	v_add_f32_e32 v205, v205, v133
	v_mov_b32_e32 v133, v205
	v_add_f32_e32 v200, v200, v134
	v_mov_b32_e32 v134, v200
	v_add_f32_e32 v201, v201, v135
	v_mov_b32_e32 v135, v201
	v_add_f32_e32 v202, v202, v136
	v_mov_b32_e32 v136, v202
	v_add_f32_e32 v203, v203, v137
	v_mov_b32_e32 v137, v203
	s_nop 1
	v_permlane32_swap_b32_e32 v190, v130
	v_permlane32_swap_b32_e32 v191, v131
	v_permlane32_swap_b32_e32 v204, v132
	v_permlane32_swap_b32_e32 v205, v133
	v_permlane32_swap_b32_e32 v200, v134
	v_permlane32_swap_b32_e32 v201, v135
	v_permlane32_swap_b32_e32 v202, v136
	v_permlane32_swap_b32_e32 v203, v137
	s_and_saveexec_b64 s[28:29], s[78:79]
	v_add_f32_e32 v190, v190, v130
	v_add_f32_e32 v191, v191, v131
	v_add_f32_e32 v204, v204, v132
	v_add_f32_e32 v205, v205, v133
	v_add_f32_e32 v200, v200, v134
	v_add_f32_e32 v201, v201, v135
	v_add_f32_e32 v202, v202, v136
	v_add_f32_e32 v203, v203, v137
	global_atomic_add_f32 v100, v190, s[30:31]
	global_atomic_add_f32 v100, v191, s[30:31] offset:64
	global_atomic_add_f32 v100, v204, s[30:31] offset:128
	global_atomic_add_f32 v100, v205, s[30:31] offset:192
	global_atomic_add_f32 v100, v200, s[30:31] offset:512
	global_atomic_add_f32 v100, v201, s[30:31] offset:576
	global_atomic_add_f32 v100, v202, s[30:31] offset:640
	global_atomic_add_f32 v100, v203, s[30:31] offset:704
	s_or_b64 exec, exec, s[28:29]
	s_mov_b64 s[30:31], exec
	s_branch .LBB0_218
.LBB0_200:
	s_add_i32 s1, s34, s65
	v_readfirstlane_b32 s4, v182
	v_mbcnt_lo_u32_b32 v100, -1, 0
	v_mbcnt_hi_u32_b32 v100, -1, v100
	s_lshl_b32 s30, s1, 11
	s_lshl_b32 s31, s4, 1
	s_add_i32 s30, s30, s31
	s_add_u32 s30, s58, s30
	s_addc_u32 s31, s59, 0
	s_mov_b64 s[28:29], s[30:31]
	v_lshrrev_b32_e32 v234, 2, v100
	v_and_b32_e32 v212, 3, v100
	v_lshlrev_b32_e32 v212, 4, v212
	v_lshl_or_b32 v234, v234, 11, v212
	global_load_dwordx4 v[130:133], v234, s[30:31]
	global_load_dwordx4 v[134:137], v234, s[30:31] offset:256
	s_add_u32 s30, s30, 0x8000
	s_addc_u32 s31, s31, 0
	global_load_dwordx4 v[138:141], v234, s[30:31]
	global_load_dwordx4 v[142:145], v234, s[30:31] offset:256
	s_add_u32 s30, s30, 0x8000
	s_addc_u32 s31, s31, 0
	global_load_dwordx4 v[146:149], v234, s[30:31]
	global_load_dwordx4 v[150:153], v234, s[30:31] offset:256
	s_add_u32 s30, s30, 0x8000
	s_addc_u32 s31, s31, 0
	global_load_dwordx4 v[154:157], v234, s[30:31]
	global_load_dwordx4 v[158:161], v234, s[30:31] offset:256
	s_add_u32 s30, s30, 0x28000
	s_addc_u32 s31, s31, 0
	global_load_dwordx4 v[162:165], v234, s[30:31]
	global_load_dwordx4 v[166:169], v234, s[30:31] offset:256
	s_add_u32 s30, s30, 0x8000
	s_addc_u32 s31, s31, 0
	global_load_dwordx4 v[182:185], v234, s[30:31]
	global_load_dwordx4 v[186:189], v234, s[30:31] offset:256
	s_add_u32 s30, s30, 0x8000
	s_addc_u32 s31, s31, 0
	global_load_dwordx4 v[200:203], v234, s[30:31]
	global_load_dwordx4 v[208:211], v234, s[30:31] offset:256
	s_add_u32 s30, s30, 0x8000
	s_addc_u32 s31, s31, 0
	global_load_dwordx4 v[226:229], v234, s[30:31]
	global_load_dwordx4 v[230:233], v234, s[30:31] offset:256
	v_and_b32_e32 v212, 15, v100
	v_lshrrev_b32_e32 v213, 4, v100
	v_lshlrev_b32_e32 v213, 2, v213
	v_lshl_or_b32 v212, v212, 4, v213
	v_and_b32_e32 v192, 3, v100
	v_lshlrev_b32_e32 v192, 6, v192
	v_and_or_b32 v213, v100, 60, v192
	v_lshlrev_b32_e32 v100, 2, v100
	s_waitcnt vmcnt(15)
	ds_bpermute_b32 v130, v212, v130
	ds_bpermute_b32 v131, v212, v131
	ds_bpermute_b32 v132, v212, v132
	ds_bpermute_b32 v133, v212, v133
	s_waitcnt vmcnt(14)
	ds_bpermute_b32 v134, v212, v134
	ds_bpermute_b32 v135, v212, v135
	ds_bpermute_b32 v136, v212, v136
	ds_bpermute_b32 v137, v212, v137
	s_waitcnt lgkmcnt(4)
	v_mov_b32_e32 v192, 0
	v_mov_b32_e32 v193, 0
	v_lshlrev_b32_e32 v204, 16, v130
	v_and_b32_e32 v205, 0xffff0000, v130
	v_pk_add_f32 v[126:127], v[126:127], v[204:205]
	v_pk_fma_f32 v[192:193], v[126:127], v[126:127], v[192:193]
	v_lshlrev_b32_e32 v190, 16, v131
	v_and_b32_e32 v191, 0xffff0000, v131
	v_pk_add_f32 v[128:129], v[128:129], v[190:191]
	v_pk_fma_f32 v[192:193], v[128:129], v[128:129], v[192:193]
	v_lshlrev_b32_e32 v204, 16, v132
	v_and_b32_e32 v205, 0xffff0000, v132
	v_pk_add_f32 v[122:123], v[122:123], v[204:205]
	v_pk_fma_f32 v[192:193], v[122:123], v[122:123], v[192:193]
	v_lshlrev_b32_e32 v190, 16, v133
	v_and_b32_e32 v191, 0xffff0000, v133
	v_pk_add_f32 v[124:125], v[124:125], v[190:191]
	v_pk_fma_f32 v[192:193], v[124:125], v[124:125], v[192:193]
	v_cvt_pk_bf16_f32 v126, v126, v127
	v_cvt_pk_bf16_f32 v127, v128, v129
	v_cvt_pk_bf16_f32 v128, v122, v123
	v_cvt_pk_bf16_f32 v129, v124, v125
	ds_bpermute_b32 v122, v213, v126
	ds_bpermute_b32 v123, v213, v127
	ds_bpermute_b32 v124, v213, v128
	ds_bpermute_b32 v125, v213, v129
	s_waitcnt vmcnt(13)
	ds_bpermute_b32 v138, v212, v138
	ds_bpermute_b32 v139, v212, v139
	ds_bpermute_b32 v140, v212, v140
	ds_bpermute_b32 v141, v212, v141
	s_waitcnt lgkmcnt(8)
	v_lshlrev_b32_e32 v204, 16, v134
	v_and_b32_e32 v205, 0xffff0000, v134
	v_pk_add_f32 v[118:119], v[118:119], v[204:205]
	v_pk_fma_f32 v[192:193], v[118:119], v[118:119], v[192:193]
	v_lshlrev_b32_e32 v190, 16, v135
	v_and_b32_e32 v191, 0xffff0000, v135
	v_pk_add_f32 v[120:121], v[120:121], v[190:191]
	v_pk_fma_f32 v[192:193], v[120:121], v[120:121], v[192:193]
	v_lshlrev_b32_e32 v204, 16, v136
	v_and_b32_e32 v205, 0xffff0000, v136
	v_pk_add_f32 v[114:115], v[114:115], v[204:205]
	v_pk_fma_f32 v[192:193], v[114:115], v[114:115], v[192:193]
	v_lshlrev_b32_e32 v190, 16, v137
	v_and_b32_e32 v191, 0xffff0000, v137
	v_pk_add_f32 v[116:117], v[116:117], v[190:191]
	v_pk_fma_f32 v[192:193], v[116:117], v[116:117], v[192:193]
	v_cvt_pk_bf16_f32 v118, v118, v119
	v_cvt_pk_bf16_f32 v119, v120, v121
	v_cvt_pk_bf16_f32 v120, v114, v115
	v_cvt_pk_bf16_f32 v121, v116, v117
	ds_bpermute_b32 v114, v213, v118
	ds_bpermute_b32 v115, v213, v119
	ds_bpermute_b32 v116, v213, v120
	ds_bpermute_b32 v117, v213, v121
	v_add_f32_e32 v130, v192, v193
	s_waitcnt lgkmcnt(8)
	global_store_dwordx4 v234, v[122:125], s[28:29]
	s_waitcnt vmcnt(13)
	ds_bpermute_b32 v142, v212, v142
	ds_bpermute_b32 v143, v212, v143
	ds_bpermute_b32 v144, v212, v144
	ds_bpermute_b32 v145, v212, v145
	s_waitcnt lgkmcnt(8)
	v_mov_b32_e32 v192, 0
	v_mov_b32_e32 v193, 0
	v_lshlrev_b32_e32 v204, 16, v138
	v_and_b32_e32 v205, 0xffff0000, v138
	v_pk_add_f32 v[110:111], v[110:111], v[204:205]
	v_pk_fma_f32 v[192:193], v[110:111], v[110:111], v[192:193]
	v_lshlrev_b32_e32 v190, 16, v139
	v_and_b32_e32 v191, 0xffff0000, v139
	v_pk_add_f32 v[112:113], v[112:113], v[190:191]
	v_pk_fma_f32 v[192:193], v[112:113], v[112:113], v[192:193]
	v_lshlrev_b32_e32 v204, 16, v140
	v_and_b32_e32 v205, 0xffff0000, v140
	v_pk_add_f32 v[106:107], v[106:107], v[204:205]
	v_pk_fma_f32 v[192:193], v[106:107], v[106:107], v[192:193]
	v_lshlrev_b32_e32 v190, 16, v141
	v_and_b32_e32 v191, 0xffff0000, v141
	v_pk_add_f32 v[108:109], v[108:109], v[190:191]
	v_pk_fma_f32 v[192:193], v[108:109], v[108:109], v[192:193]
	v_cvt_pk_bf16_f32 v110, v110, v111
	v_cvt_pk_bf16_f32 v111, v112, v113
	v_cvt_pk_bf16_f32 v112, v106, v107
	v_cvt_pk_bf16_f32 v113, v108, v109
	ds_bpermute_b32 v106, v213, v110
	ds_bpermute_b32 v107, v213, v111
	ds_bpermute_b32 v108, v213, v112
	ds_bpermute_b32 v109, v213, v113
	s_waitcnt lgkmcnt(8)
	global_store_dwordx4 v234, v[114:117], s[28:29] offset:256
	s_add_u32 s28, s28, 0x8000
	s_addc_u32 s29, s29, 0
	s_waitcnt vmcnt(13)
	ds_bpermute_b32 v146, v212, v146
	ds_bpermute_b32 v147, v212, v147
	ds_bpermute_b32 v148, v212, v148
	ds_bpermute_b32 v149, v212, v149
	s_waitcnt lgkmcnt(8)
	v_lshlrev_b32_e32 v204, 16, v142
	v_and_b32_e32 v205, 0xffff0000, v142
	v_pk_add_f32 v[102:103], v[102:103], v[204:205]
	v_pk_fma_f32 v[192:193], v[102:103], v[102:103], v[192:193]
	v_lshlrev_b32_e32 v190, 16, v143
	v_and_b32_e32 v191, 0xffff0000, v143
	v_pk_add_f32 v[104:105], v[104:105], v[190:191]
	v_pk_fma_f32 v[192:193], v[104:105], v[104:105], v[192:193]
	v_lshlrev_b32_e32 v204, 16, v144
	v_and_b32_e32 v205, 0xffff0000, v144
	v_pk_add_f32 v[96:97], v[96:97], v[204:205]
	v_pk_fma_f32 v[192:193], v[96:97], v[96:97], v[192:193]
	v_lshlrev_b32_e32 v190, 16, v145
	v_and_b32_e32 v191, 0xffff0000, v145
	v_pk_add_f32 v[98:99], v[98:99], v[190:191]
	v_pk_fma_f32 v[192:193], v[98:99], v[98:99], v[192:193]
	v_cvt_pk_bf16_f32 v102, v102, v103
	v_cvt_pk_bf16_f32 v103, v104, v105
	v_cvt_pk_bf16_f32 v104, v96, v97
	v_cvt_pk_bf16_f32 v105, v98, v99
	ds_bpermute_b32 v96, v213, v102
	ds_bpermute_b32 v97, v213, v103
	ds_bpermute_b32 v98, v213, v104
	ds_bpermute_b32 v99, v213, v105
	v_add_f32_e32 v138, v192, v193
	s_waitcnt lgkmcnt(8)
	global_store_dwordx4 v234, v[106:109], s[28:29]
	s_waitcnt vmcnt(13)
	ds_bpermute_b32 v150, v212, v150
	ds_bpermute_b32 v151, v212, v151
	ds_bpermute_b32 v152, v212, v152
	ds_bpermute_b32 v153, v212, v153
	s_waitcnt lgkmcnt(8)
	v_mov_b32_e32 v192, 0
	v_mov_b32_e32 v193, 0
	v_lshlrev_b32_e32 v204, 16, v146
	v_and_b32_e32 v205, 0xffff0000, v146
	v_pk_add_f32 v[92:93], v[92:93], v[204:205]
	v_pk_fma_f32 v[192:193], v[92:93], v[92:93], v[192:193]
	v_lshlrev_b32_e32 v190, 16, v147
	v_and_b32_e32 v191, 0xffff0000, v147
	v_pk_add_f32 v[94:95], v[94:95], v[190:191]
	v_pk_fma_f32 v[192:193], v[94:95], v[94:95], v[192:193]
	v_lshlrev_b32_e32 v204, 16, v148
	v_and_b32_e32 v205, 0xffff0000, v148
	v_pk_add_f32 v[88:89], v[88:89], v[204:205]
	v_pk_fma_f32 v[192:193], v[88:89], v[88:89], v[192:193]
	v_lshlrev_b32_e32 v190, 16, v149
	v_and_b32_e32 v191, 0xffff0000, v149
	v_pk_add_f32 v[90:91], v[90:91], v[190:191]
	v_pk_fma_f32 v[192:193], v[90:91], v[90:91], v[192:193]
	v_cvt_pk_bf16_f32 v92, v92, v93
	v_cvt_pk_bf16_f32 v93, v94, v95
	v_cvt_pk_bf16_f32 v94, v88, v89
	v_cvt_pk_bf16_f32 v95, v90, v91
	ds_bpermute_b32 v88, v213, v92
	ds_bpermute_b32 v89, v213, v93
	ds_bpermute_b32 v90, v213, v94
	ds_bpermute_b32 v91, v213, v95
	s_waitcnt lgkmcnt(8)
	global_store_dwordx4 v234, v[96:99], s[28:29] offset:256
	s_add_u32 s28, s28, 0x8000
	s_addc_u32 s29, s29, 0
	s_waitcnt vmcnt(13)
	ds_bpermute_b32 v154, v212, v154
	ds_bpermute_b32 v155, v212, v155
	ds_bpermute_b32 v156, v212, v156
	ds_bpermute_b32 v157, v212, v157
	s_waitcnt lgkmcnt(8)
	v_lshlrev_b32_e32 v204, 16, v150
	v_and_b32_e32 v205, 0xffff0000, v150
	v_pk_add_f32 v[84:85], v[84:85], v[204:205]
	v_pk_fma_f32 v[192:193], v[84:85], v[84:85], v[192:193]
	v_lshlrev_b32_e32 v190, 16, v151
	v_and_b32_e32 v191, 0xffff0000, v151
	v_pk_add_f32 v[86:87], v[86:87], v[190:191]
	v_pk_fma_f32 v[192:193], v[86:87], v[86:87], v[192:193]
	v_lshlrev_b32_e32 v204, 16, v152
	v_and_b32_e32 v205, 0xffff0000, v152
	v_pk_add_f32 v[80:81], v[80:81], v[204:205]
	v_pk_fma_f32 v[192:193], v[80:81], v[80:81], v[192:193]
	v_lshlrev_b32_e32 v190, 16, v153
	v_and_b32_e32 v191, 0xffff0000, v153
	v_pk_add_f32 v[82:83], v[82:83], v[190:191]
	v_pk_fma_f32 v[192:193], v[82:83], v[82:83], v[192:193]
	v_cvt_pk_bf16_f32 v84, v84, v85
	v_cvt_pk_bf16_f32 v85, v86, v87
	v_cvt_pk_bf16_f32 v86, v80, v81
	v_cvt_pk_bf16_f32 v87, v82, v83
	ds_bpermute_b32 v80, v213, v84
	ds_bpermute_b32 v81, v213, v85
	ds_bpermute_b32 v82, v213, v86
	ds_bpermute_b32 v83, v213, v87
	v_add_f32_e32 v146, v192, v193
	s_waitcnt lgkmcnt(8)
	global_store_dwordx4 v234, v[88:91], s[28:29]
	s_waitcnt vmcnt(13)
	ds_bpermute_b32 v158, v212, v158
	ds_bpermute_b32 v159, v212, v159
	ds_bpermute_b32 v160, v212, v160
	ds_bpermute_b32 v161, v212, v161
	s_waitcnt lgkmcnt(8)
	v_mov_b32_e32 v192, 0
	v_mov_b32_e32 v193, 0
	v_lshlrev_b32_e32 v204, 16, v154
	v_and_b32_e32 v205, 0xffff0000, v154
	v_pk_add_f32 v[76:77], v[76:77], v[204:205]
	v_pk_fma_f32 v[192:193], v[76:77], v[76:77], v[192:193]
	v_lshlrev_b32_e32 v190, 16, v155
	v_and_b32_e32 v191, 0xffff0000, v155
	v_pk_add_f32 v[78:79], v[78:79], v[190:191]
	v_pk_fma_f32 v[192:193], v[78:79], v[78:79], v[192:193]
	v_lshlrev_b32_e32 v204, 16, v156
	v_and_b32_e32 v205, 0xffff0000, v156
	v_pk_add_f32 v[72:73], v[72:73], v[204:205]
	v_pk_fma_f32 v[192:193], v[72:73], v[72:73], v[192:193]
	v_lshlrev_b32_e32 v190, 16, v157
	v_and_b32_e32 v191, 0xffff0000, v157
	v_pk_add_f32 v[74:75], v[74:75], v[190:191]
	v_pk_fma_f32 v[192:193], v[74:75], v[74:75], v[192:193]
	v_cvt_pk_bf16_f32 v76, v76, v77
	v_cvt_pk_bf16_f32 v77, v78, v79
	v_cvt_pk_bf16_f32 v78, v72, v73
	v_cvt_pk_bf16_f32 v79, v74, v75
	ds_bpermute_b32 v72, v213, v76
	ds_bpermute_b32 v73, v213, v77
	ds_bpermute_b32 v74, v213, v78
	ds_bpermute_b32 v75, v213, v79
	s_waitcnt lgkmcnt(8)
	global_store_dwordx4 v234, v[80:83], s[28:29] offset:256
	s_add_u32 s28, s28, 0x8000
	s_addc_u32 s29, s29, 0
	s_waitcnt vmcnt(13)
	ds_bpermute_b32 v162, v212, v162
	ds_bpermute_b32 v163, v212, v163
	ds_bpermute_b32 v164, v212, v164
	ds_bpermute_b32 v165, v212, v165
	s_waitcnt lgkmcnt(8)
	v_lshlrev_b32_e32 v204, 16, v158
	v_and_b32_e32 v205, 0xffff0000, v158
	v_pk_add_f32 v[68:69], v[68:69], v[204:205]
	v_pk_fma_f32 v[192:193], v[68:69], v[68:69], v[192:193]
	v_lshlrev_b32_e32 v190, 16, v159
	v_and_b32_e32 v191, 0xffff0000, v159
	v_pk_add_f32 v[70:71], v[70:71], v[190:191]
	v_pk_fma_f32 v[192:193], v[70:71], v[70:71], v[192:193]
	v_lshlrev_b32_e32 v204, 16, v160
	v_and_b32_e32 v205, 0xffff0000, v160
	v_pk_add_f32 v[64:65], v[64:65], v[204:205]
	v_pk_fma_f32 v[192:193], v[64:65], v[64:65], v[192:193]
	v_lshlrev_b32_e32 v190, 16, v161
	v_and_b32_e32 v191, 0xffff0000, v161
	v_pk_add_f32 v[66:67], v[66:67], v[190:191]
	v_pk_fma_f32 v[192:193], v[66:67], v[66:67], v[192:193]
	v_cvt_pk_bf16_f32 v68, v68, v69
	v_cvt_pk_bf16_f32 v69, v70, v71
	v_cvt_pk_bf16_f32 v70, v64, v65
	v_cvt_pk_bf16_f32 v71, v66, v67
	ds_bpermute_b32 v64, v213, v68
	ds_bpermute_b32 v65, v213, v69
	ds_bpermute_b32 v66, v213, v70
	ds_bpermute_b32 v67, v213, v71
	v_add_f32_e32 v154, v192, v193
	s_waitcnt lgkmcnt(8)
	global_store_dwordx4 v234, v[72:75], s[28:29]
	s_waitcnt vmcnt(13)
	ds_bpermute_b32 v166, v212, v166
	ds_bpermute_b32 v167, v212, v167
	ds_bpermute_b32 v168, v212, v168
	ds_bpermute_b32 v169, v212, v169
	s_waitcnt lgkmcnt(8)
	v_mov_b32_e32 v192, 0
	v_mov_b32_e32 v193, 0
	v_lshlrev_b32_e32 v204, 16, v162
	v_and_b32_e32 v205, 0xffff0000, v162
	v_pk_add_f32 v[60:61], v[60:61], v[204:205]
	v_pk_fma_f32 v[192:193], v[60:61], v[60:61], v[192:193]
	v_lshlrev_b32_e32 v190, 16, v163
	v_and_b32_e32 v191, 0xffff0000, v163
	v_pk_add_f32 v[62:63], v[62:63], v[190:191]
	v_pk_fma_f32 v[192:193], v[62:63], v[62:63], v[192:193]
	v_lshlrev_b32_e32 v204, 16, v164
	v_and_b32_e32 v205, 0xffff0000, v164
	v_pk_add_f32 v[56:57], v[56:57], v[204:205]
	v_pk_fma_f32 v[192:193], v[56:57], v[56:57], v[192:193]
	v_lshlrev_b32_e32 v190, 16, v165
	v_and_b32_e32 v191, 0xffff0000, v165
	v_pk_add_f32 v[58:59], v[58:59], v[190:191]
	v_pk_fma_f32 v[192:193], v[58:59], v[58:59], v[192:193]
	v_cvt_pk_bf16_f32 v60, v60, v61
	v_cvt_pk_bf16_f32 v61, v62, v63
	v_cvt_pk_bf16_f32 v62, v56, v57
	v_cvt_pk_bf16_f32 v63, v58, v59
	ds_bpermute_b32 v56, v213, v60
	ds_bpermute_b32 v57, v213, v61
	ds_bpermute_b32 v58, v213, v62
	ds_bpermute_b32 v59, v213, v63
	s_waitcnt lgkmcnt(8)
	global_store_dwordx4 v234, v[64:67], s[28:29] offset:256
	s_add_u32 s28, s28, 0x28000
	s_addc_u32 s29, s29, 0
	s_waitcnt vmcnt(13)
	ds_bpermute_b32 v182, v212, v182
	ds_bpermute_b32 v183, v212, v183
	ds_bpermute_b32 v184, v212, v184
	ds_bpermute_b32 v185, v212, v185
	s_waitcnt lgkmcnt(8)
	v_lshlrev_b32_e32 v204, 16, v166
	v_and_b32_e32 v205, 0xffff0000, v166
	v_pk_add_f32 v[52:53], v[52:53], v[204:205]
	v_pk_fma_f32 v[192:193], v[52:53], v[52:53], v[192:193]
	v_lshlrev_b32_e32 v190, 16, v167
	v_and_b32_e32 v191, 0xffff0000, v167
	v_pk_add_f32 v[54:55], v[54:55], v[190:191]
	v_pk_fma_f32 v[192:193], v[54:55], v[54:55], v[192:193]
	v_lshlrev_b32_e32 v204, 16, v168
	v_and_b32_e32 v205, 0xffff0000, v168
	v_pk_add_f32 v[48:49], v[48:49], v[204:205]
	v_pk_fma_f32 v[192:193], v[48:49], v[48:49], v[192:193]
	v_lshlrev_b32_e32 v190, 16, v169
	v_and_b32_e32 v191, 0xffff0000, v169
	v_pk_add_f32 v[50:51], v[50:51], v[190:191]
	v_pk_fma_f32 v[192:193], v[50:51], v[50:51], v[192:193]
	v_cvt_pk_bf16_f32 v52, v52, v53
	v_cvt_pk_bf16_f32 v53, v54, v55
	v_cvt_pk_bf16_f32 v54, v48, v49
	v_cvt_pk_bf16_f32 v55, v50, v51
	ds_bpermute_b32 v48, v213, v52
	ds_bpermute_b32 v49, v213, v53
	ds_bpermute_b32 v50, v213, v54
	ds_bpermute_b32 v51, v213, v55
	v_add_f32_e32 v162, v192, v193
	s_waitcnt lgkmcnt(8)
	global_store_dwordx4 v234, v[56:59], s[28:29]
	s_waitcnt vmcnt(13)
	ds_bpermute_b32 v186, v212, v186
	ds_bpermute_b32 v187, v212, v187
	ds_bpermute_b32 v188, v212, v188
	ds_bpermute_b32 v189, v212, v189
	s_waitcnt lgkmcnt(8)
	v_mov_b32_e32 v192, 0
	v_mov_b32_e32 v193, 0
	v_lshlrev_b32_e32 v204, 16, v182
	v_and_b32_e32 v205, 0xffff0000, v182
	v_pk_add_f32 v[44:45], v[44:45], v[204:205]
	v_pk_fma_f32 v[192:193], v[44:45], v[44:45], v[192:193]
	v_lshlrev_b32_e32 v190, 16, v183
	v_and_b32_e32 v191, 0xffff0000, v183
	v_pk_add_f32 v[46:47], v[46:47], v[190:191]
	v_pk_fma_f32 v[192:193], v[46:47], v[46:47], v[192:193]
	v_lshlrev_b32_e32 v204, 16, v184
	v_and_b32_e32 v205, 0xffff0000, v184
	v_pk_add_f32 v[40:41], v[40:41], v[204:205]
	v_pk_fma_f32 v[192:193], v[40:41], v[40:41], v[192:193]
	v_lshlrev_b32_e32 v190, 16, v185
	v_and_b32_e32 v191, 0xffff0000, v185
	v_pk_add_f32 v[42:43], v[42:43], v[190:191]
	v_pk_fma_f32 v[192:193], v[42:43], v[42:43], v[192:193]
	v_cvt_pk_bf16_f32 v44, v44, v45
	v_cvt_pk_bf16_f32 v45, v46, v47
	v_cvt_pk_bf16_f32 v46, v40, v41
	v_cvt_pk_bf16_f32 v47, v42, v43
	ds_bpermute_b32 v40, v213, v44
	ds_bpermute_b32 v41, v213, v45
	ds_bpermute_b32 v42, v213, v46
	ds_bpermute_b32 v43, v213, v47
	s_waitcnt lgkmcnt(8)
	global_store_dwordx4 v234, v[48:51], s[28:29] offset:256
	s_add_u32 s28, s28, 0x8000
	s_addc_u32 s29, s29, 0
	s_waitcnt vmcnt(13)
	ds_bpermute_b32 v200, v212, v200
	ds_bpermute_b32 v201, v212, v201
	ds_bpermute_b32 v202, v212, v202
	ds_bpermute_b32 v203, v212, v203
	s_waitcnt lgkmcnt(8)
	v_lshlrev_b32_e32 v204, 16, v186
	v_and_b32_e32 v205, 0xffff0000, v186
	v_pk_add_f32 v[36:37], v[36:37], v[204:205]
	v_pk_fma_f32 v[192:193], v[36:37], v[36:37], v[192:193]
	v_lshlrev_b32_e32 v190, 16, v187
	v_and_b32_e32 v191, 0xffff0000, v187
	v_pk_add_f32 v[38:39], v[38:39], v[190:191]
	v_pk_fma_f32 v[192:193], v[38:39], v[38:39], v[192:193]
	v_lshlrev_b32_e32 v204, 16, v188
	v_and_b32_e32 v205, 0xffff0000, v188
	v_pk_add_f32 v[32:33], v[32:33], v[204:205]
	v_pk_fma_f32 v[192:193], v[32:33], v[32:33], v[192:193]
	v_lshlrev_b32_e32 v190, 16, v189
	v_and_b32_e32 v191, 0xffff0000, v189
	v_pk_add_f32 v[34:35], v[34:35], v[190:191]
	v_pk_fma_f32 v[192:193], v[34:35], v[34:35], v[192:193]
	v_cvt_pk_bf16_f32 v36, v36, v37
	v_cvt_pk_bf16_f32 v37, v38, v39
	v_cvt_pk_bf16_f32 v38, v32, v33
	v_cvt_pk_bf16_f32 v39, v34, v35
	ds_bpermute_b32 v32, v213, v36
	ds_bpermute_b32 v33, v213, v37
	ds_bpermute_b32 v34, v213, v38
	ds_bpermute_b32 v35, v213, v39
	v_add_f32_e32 v182, v192, v193
	s_waitcnt lgkmcnt(8)
	global_store_dwordx4 v234, v[40:43], s[28:29]
	s_waitcnt vmcnt(13)
	ds_bpermute_b32 v208, v212, v208
	ds_bpermute_b32 v209, v212, v209
	ds_bpermute_b32 v210, v212, v210
	ds_bpermute_b32 v211, v212, v211
	s_waitcnt lgkmcnt(8)
	v_mov_b32_e32 v192, 0
	v_mov_b32_e32 v193, 0
	v_lshlrev_b32_e32 v204, 16, v200
	v_and_b32_e32 v205, 0xffff0000, v200
	v_pk_add_f32 v[28:29], v[28:29], v[204:205]
	v_pk_fma_f32 v[192:193], v[28:29], v[28:29], v[192:193]
	v_lshlrev_b32_e32 v190, 16, v201
	v_and_b32_e32 v191, 0xffff0000, v201
	v_pk_add_f32 v[30:31], v[30:31], v[190:191]
	v_pk_fma_f32 v[192:193], v[30:31], v[30:31], v[192:193]
	v_lshlrev_b32_e32 v204, 16, v202
	v_and_b32_e32 v205, 0xffff0000, v202
	v_pk_add_f32 v[24:25], v[24:25], v[204:205]
	v_pk_fma_f32 v[192:193], v[24:25], v[24:25], v[192:193]
	v_lshlrev_b32_e32 v190, 16, v203
	v_and_b32_e32 v191, 0xffff0000, v203
	v_pk_add_f32 v[26:27], v[26:27], v[190:191]
	v_pk_fma_f32 v[192:193], v[26:27], v[26:27], v[192:193]
	v_cvt_pk_bf16_f32 v28, v28, v29
	v_cvt_pk_bf16_f32 v29, v30, v31
	v_cvt_pk_bf16_f32 v30, v24, v25
	v_cvt_pk_bf16_f32 v31, v26, v27
	ds_bpermute_b32 v24, v213, v28
	ds_bpermute_b32 v25, v213, v29
	ds_bpermute_b32 v26, v213, v30
	ds_bpermute_b32 v27, v213, v31
	s_waitcnt lgkmcnt(8)
	global_store_dwordx4 v234, v[32:35], s[28:29] offset:256
	s_add_u32 s28, s28, 0x8000
	s_addc_u32 s29, s29, 0
	s_waitcnt vmcnt(13)
	ds_bpermute_b32 v226, v212, v226
	ds_bpermute_b32 v227, v212, v227
	ds_bpermute_b32 v228, v212, v228
	ds_bpermute_b32 v229, v212, v229
	s_waitcnt lgkmcnt(8)
	v_lshlrev_b32_e32 v204, 16, v208
	v_and_b32_e32 v205, 0xffff0000, v208
	v_pk_add_f32 v[20:21], v[20:21], v[204:205]
	v_pk_fma_f32 v[192:193], v[20:21], v[20:21], v[192:193]
	v_lshlrev_b32_e32 v190, 16, v209
	v_and_b32_e32 v191, 0xffff0000, v209
	v_pk_add_f32 v[22:23], v[22:23], v[190:191]
	v_pk_fma_f32 v[192:193], v[22:23], v[22:23], v[192:193]
	v_lshlrev_b32_e32 v204, 16, v210
	v_and_b32_e32 v205, 0xffff0000, v210
	v_pk_add_f32 v[16:17], v[16:17], v[204:205]
	v_pk_fma_f32 v[192:193], v[16:17], v[16:17], v[192:193]
	v_lshlrev_b32_e32 v190, 16, v211
	v_and_b32_e32 v191, 0xffff0000, v211
	v_pk_add_f32 v[18:19], v[18:19], v[190:191]
	v_pk_fma_f32 v[192:193], v[18:19], v[18:19], v[192:193]
	v_cvt_pk_bf16_f32 v20, v20, v21
	v_cvt_pk_bf16_f32 v21, v22, v23
	v_cvt_pk_bf16_f32 v22, v16, v17
	v_cvt_pk_bf16_f32 v23, v18, v19
	ds_bpermute_b32 v16, v213, v20
	ds_bpermute_b32 v17, v213, v21
	ds_bpermute_b32 v18, v213, v22
	ds_bpermute_b32 v19, v213, v23
	v_add_f32_e32 v200, v192, v193
	s_waitcnt lgkmcnt(8)
	global_store_dwordx4 v234, v[24:27], s[28:29]
	s_waitcnt vmcnt(13)
	ds_bpermute_b32 v230, v212, v230
	ds_bpermute_b32 v231, v212, v231
	ds_bpermute_b32 v232, v212, v232
	ds_bpermute_b32 v233, v212, v233
	s_waitcnt lgkmcnt(8)
	v_mov_b32_e32 v192, 0
	v_mov_b32_e32 v193, 0
	v_lshlrev_b32_e32 v204, 16, v226
	v_and_b32_e32 v205, 0xffff0000, v226
	v_pk_add_f32 v[12:13], v[12:13], v[204:205]
	v_pk_fma_f32 v[192:193], v[12:13], v[12:13], v[192:193]
	v_lshlrev_b32_e32 v190, 16, v227
	v_and_b32_e32 v191, 0xffff0000, v227
	v_pk_add_f32 v[14:15], v[14:15], v[190:191]
	v_pk_fma_f32 v[192:193], v[14:15], v[14:15], v[192:193]
	v_lshlrev_b32_e32 v204, 16, v228
	v_and_b32_e32 v205, 0xffff0000, v228
	v_pk_add_f32 v[8:9], v[8:9], v[204:205]
	v_pk_fma_f32 v[192:193], v[8:9], v[8:9], v[192:193]
	v_lshlrev_b32_e32 v190, 16, v229
	v_and_b32_e32 v191, 0xffff0000, v229
	v_pk_add_f32 v[10:11], v[10:11], v[190:191]
	v_pk_fma_f32 v[192:193], v[10:11], v[10:11], v[192:193]
	v_cvt_pk_bf16_f32 v12, v12, v13
	v_cvt_pk_bf16_f32 v13, v14, v15
	v_cvt_pk_bf16_f32 v14, v8, v9
	v_cvt_pk_bf16_f32 v15, v10, v11
	ds_bpermute_b32 v8, v213, v12
	ds_bpermute_b32 v9, v213, v13
	ds_bpermute_b32 v10, v213, v14
	ds_bpermute_b32 v11, v213, v15
	s_waitcnt lgkmcnt(8)
	global_store_dwordx4 v234, v[16:19], s[28:29] offset:256
	s_add_u32 s28, s28, 0x8000
	s_addc_u32 s29, s29, 0
	s_waitcnt lgkmcnt(4)
	v_lshlrev_b32_e32 v204, 16, v230
	v_and_b32_e32 v205, 0xffff0000, v230
	v_pk_add_f32 v[4:5], v[4:5], v[204:205]
	v_pk_fma_f32 v[192:193], v[4:5], v[4:5], v[192:193]
	v_lshlrev_b32_e32 v190, 16, v231
	v_and_b32_e32 v191, 0xffff0000, v231
	v_pk_add_f32 v[6:7], v[6:7], v[190:191]
	v_pk_fma_f32 v[192:193], v[6:7], v[6:7], v[192:193]
	v_lshlrev_b32_e32 v204, 16, v232
	v_and_b32_e32 v205, 0xffff0000, v232
	v_pk_add_f32 v[0:1], v[0:1], v[204:205]
	v_pk_fma_f32 v[192:193], v[0:1], v[0:1], v[192:193]
	v_lshlrev_b32_e32 v190, 16, v233
	v_and_b32_e32 v191, 0xffff0000, v233
	v_pk_add_f32 v[2:3], v[2:3], v[190:191]
	v_pk_fma_f32 v[192:193], v[2:3], v[2:3], v[192:193]
	v_cvt_pk_bf16_f32 v4, v4, v5
	v_cvt_pk_bf16_f32 v5, v6, v7
	v_cvt_pk_bf16_f32 v6, v0, v1
	v_cvt_pk_bf16_f32 v7, v2, v3
	ds_bpermute_b32 v0, v213, v4
	ds_bpermute_b32 v1, v213, v5
	ds_bpermute_b32 v2, v213, v6
	ds_bpermute_b32 v3, v213, v7
	v_add_f32_e32 v226, v192, v193
	s_waitcnt lgkmcnt(4)
	global_store_dwordx4 v234, v[8:11], s[28:29]
	s_waitcnt lgkmcnt(0)
	global_store_dwordx4 v234, v[0:3], s[28:29] offset:256
	ds_swizzle_b32 v131, v130 offset:swizzle(SWAP,16)
	ds_swizzle_b32 v139, v138 offset:swizzle(SWAP,16)
	ds_swizzle_b32 v147, v146 offset:swizzle(SWAP,16)
	ds_swizzle_b32 v155, v154 offset:swizzle(SWAP,16)
	ds_swizzle_b32 v163, v162 offset:swizzle(SWAP,16)
	ds_swizzle_b32 v183, v182 offset:swizzle(SWAP,16)
	ds_swizzle_b32 v201, v200 offset:swizzle(SWAP,16)
	ds_swizzle_b32 v227, v226 offset:swizzle(SWAP,16)
	s_lshl_b32 s30, s1, 2
	s_add_u32 s30, s14, s30
	s_addc_u32 s31, s15, 0
	s_waitcnt lgkmcnt(0)
	v_add_f32_e32 v130, v130, v131
	v_mov_b32_e32 v131, v130
	v_add_f32_e32 v138, v138, v139
	v_mov_b32_e32 v139, v138
	v_add_f32_e32 v146, v146, v147
	v_mov_b32_e32 v147, v146
	v_add_f32_e32 v154, v154, v155
	v_mov_b32_e32 v155, v154
	v_add_f32_e32 v162, v162, v163
	v_mov_b32_e32 v163, v162
	v_add_f32_e32 v182, v182, v183
	v_mov_b32_e32 v183, v182
	v_add_f32_e32 v200, v200, v201
	v_mov_b32_e32 v201, v200
	v_add_f32_e32 v226, v226, v227
	v_mov_b32_e32 v227, v226
	s_nop 1
	v_permlane32_swap_b32_e32 v130, v131
	v_permlane32_swap_b32_e32 v138, v139
	v_permlane32_swap_b32_e32 v146, v147
	v_permlane32_swap_b32_e32 v154, v155
	v_permlane32_swap_b32_e32 v162, v163
	v_permlane32_swap_b32_e32 v182, v183
	v_permlane32_swap_b32_e32 v200, v201
	v_permlane32_swap_b32_e32 v226, v227
	s_and_saveexec_b64 s[28:29], s[78:79]
	v_add_f32_e32 v130, v130, v131
	v_add_f32_e32 v138, v138, v139
	v_add_f32_e32 v146, v146, v147
	v_add_f32_e32 v154, v154, v155
	v_add_f32_e32 v162, v162, v163
	v_add_f32_e32 v182, v182, v183
	v_add_f32_e32 v200, v200, v201
	v_add_f32_e32 v226, v226, v227
	global_atomic_add_f32 v100, v130, s[30:31]
	global_atomic_add_f32 v100, v138, s[30:31] offset:64
	global_atomic_add_f32 v100, v146, s[30:31] offset:128
	global_atomic_add_f32 v100, v154, s[30:31] offset:192
	global_atomic_add_f32 v100, v162, s[30:31] offset:512
	global_atomic_add_f32 v100, v182, s[30:31] offset:576
	global_atomic_add_f32 v100, v200, s[30:31] offset:640
	global_atomic_add_f32 v100, v226, s[30:31] offset:704
	s_or_b64 exec, exec, s[28:29]
	s_mov_b64 s[30:31], exec
	s_branch .LBB0_218
